# v51 + row-statistic f32 atomics of the three residual epilogues deferred to the epilogue end (out of the in-order vmcnt chain), vmcnt recomputed exactly
# baseline (speedup 1.0000x reference)
.LBB0_232:
	v_lshl_add_u32 v64, s54, 8, v216
	v_lshl_or_b32 v140, s55, 8, v218
	v_ashrrev_i32_e32 v65, 31, v64
	v_readlane_b32 s60, v252, 0
	v_ashrrev_i32_e32 v141, 31, v140
	s_waitcnt lgkmcnt(0)
	v_lshlrev_b64 v[0:1], 13, v[64:65]
	v_readlane_b32 s61, v252, 1
	v_lshlrev_b64 v[16:17], 2, v[140:141]
	v_readlane_b32 s74, v252, 14
	v_lshl_add_u64 v[212:213], s[60:61], 0, v[0:1]
	v_lshl_add_u64 v[0:1], v[212:213], 0, v[16:17]
	v_readlane_b32 s75, v252, 15
	global_load_dwordx4 v[28:31], v[0:1], off
	global_load_dwordx4 v[40:43], v[0:1], off offset:64
	global_load_dwordx4 v[52:55], v[0:1], off offset:512
	v_lshl_add_u64 v[2:3], s[74:75], 0, v[16:17]
	global_load_dwordx4 v[12:15], v[2:3], off
	global_load_dwordx4 v[8:11], v[2:3], off offset:64
	global_load_dwordx4 v[4:7], v[2:3], off offset:512
	global_load_dwordx4 v[60:63], v[0:1], off offset:576
	v_or_b32_e32 v66, 16, v64
	v_or_b32_e32 v214, 32, v64
	v_ashrrev_i32_e32 v67, 31, v66
	v_ashrrev_i32_e32 v215, 31, v214
	v_lshlrev_b64 v[18:19], 13, v[66:67]
	v_lshlrev_b64 v[20:21], 13, v[214:215]
	v_lshl_add_u64 v[18:19], s[60:61], 0, v[18:19]
	v_lshl_add_u64 v[20:21], s[60:61], 0, v[20:21]
	global_load_dwordx4 v[0:3], v[2:3], off offset:576
	v_lshl_add_u64 v[18:19], v[18:19], 0, v[16:17]
	v_lshl_add_u64 v[16:17], v[20:21], 0, v[16:17]
	global_load_dwordx4 v[56:59], v[18:19], off
	global_load_dwordx4 v[48:51], v[18:19], off offset:64
	global_load_dwordx4 v[36:39], v[18:19], off offset:512
	global_load_dwordx4 v[24:27], v[18:19], off offset:576
	global_load_dwordx4 v[44:47], v[16:17], off
	global_load_dwordx4 v[32:35], v[16:17], off offset:64
	global_load_dwordx4 v[20:23], v[16:17], off offset:512
	s_nop 0
	global_load_dwordx4 v[16:19], v[16:17], off offset:576
	v_and_b32_e32 v225, 64, v223
	v_xor_b32_e32 v224, 16, v223
	v_add_u32_e32 v225, 64, v225
	v_xor_b32_e32 v226, 32, v223
	v_cmp_lt_i32_e32 vcc, v224, v225
	v_readlane_b32 s62, v252, 2
	v_readlane_b32 s63, v252, 3
	v_readlane_b32 s64, v252, 4
	v_readlane_b32 s65, v252, 5
	v_readlane_b32 s66, v252, 6
	v_readlane_b32 s67, v252, 7
	v_readlane_b32 s68, v252, 8
	v_readlane_b32 s69, v252, 9
	v_readlane_b32 s70, v252, 10
	v_readlane_b32 s71, v252, 11
	v_readlane_b32 s72, v252, 12
	v_readlane_b32 s73, v252, 13
	v_cndmask_b32_e32 v224, v223, v224, vcc
	v_cmp_lt_i32_e32 vcc, v226, v225
	v_readlane_b32 s60, v252, 16
	v_readlane_b32 s74, v252, 30
	v_cndmask_b32_e32 v228, v223, v226, vcc
	v_lshlrev_b64 v[226:227], 11, v[64:65]
	v_lshl_add_u64 v[226:227], v[226:227], 0, v[140:141]
	v_readlane_b32 s75, v252, 31
	v_lshlrev_b32_e32 v225, 2, v224
	v_lshlrev_b32_e32 v224, 2, v228
	v_lshl_add_u64 v[228:229], v[226:227], 2, s[74:75]
	v_lshlrev_b64 v[226:227], 1, v[226:227]
	v_lshl_add_u64 v[230:231], s[12:13], 0, v[226:227]
	v_or_b32_e32 v232, 32, v226
	v_mov_b32_e32 v233, v227
	v_lshl_add_u64 v[232:233], s[12:13], 0, v[232:233]
	v_readlane_b32 s61, v252, 17
	v_readlane_b32 s62, v252, 18
	v_readlane_b32 s63, v252, 19
	v_readlane_b32 s64, v252, 20
	v_readlane_b32 s65, v252, 21
	v_readlane_b32 s66, v252, 22
	v_readlane_b32 s67, v252, 23
	v_readlane_b32 s68, v252, 24
	v_readlane_b32 s69, v252, 25
	v_readlane_b32 s70, v252, 26
	v_readlane_b32 s71, v252, 27
	v_readlane_b32 s72, v252, 28
	v_readlane_b32 s73, v252, 29
	s_waitcnt vmcnt(0)
	v_pk_add_f32 v[30:31], v[200:201], v[30:31]
	v_pk_add_f32 v[28:29], v[202:203], v[28:29]
	v_pk_add_f32 v[42:43], v[204:205], v[42:43]
	v_pk_add_f32 v[40:41], v[206:207], v[40:41]
	v_pk_add_f32 v[54:55], v[210:211], v[54:55]
	v_pk_add_f32 v[52:53], v[208:209], v[52:53]
	v_mul_f32_e32 v234, v29, v29
	v_mul_f32_e32 v235, v31, v31
	v_pk_mul_f32 v[200:201], v[14:15], v[30:31]
	v_pk_mul_f32 v[202:203], v[12:13], v[28:29]
	v_mul_f32_e32 v236, v41, v41
	v_mul_f32_e32 v237, v43, v43
	global_store_dwordx4 v[228:229], v[28:31], off
	v_pk_mul_f32 v[204:205], v[10:11], v[42:43]
	v_pk_mul_f32 v[206:207], v[8:9], v[40:41]
	v_mul_f32_e32 v238, v53, v53
	v_mul_f32_e32 v239, v55, v55
	v_fmac_f32_e32 v234, v28, v28
	v_fmac_f32_e32 v235, v30, v30
	v_cvt_pk_bf16_f32 v28, v202, v203
	v_cvt_pk_bf16_f32 v29, v200, v201
	v_fmac_f32_e32 v236, v40, v40
	v_fmac_f32_e32 v237, v42, v42
	v_cvt_pk_bf16_f32 v30, v206, v207
	v_cvt_pk_bf16_f32 v31, v204, v205
	v_fmac_f32_e32 v238, v52, v52
	v_fmac_f32_e32 v239, v54, v54
	v_add_f32_e32 v200, v234, v235
	global_store_dwordx2 v[230:231], v[28:29], off
	global_store_dwordx4 v[228:229], v[40:43], off offset:64
	v_add_f32_e32 v28, v236, v237
	v_pk_mul_f32 v[208:209], v[6:7], v[54:55]
	v_pk_mul_f32 v[210:211], v[4:5], v[52:53]
	global_store_dwordx2 v[232:233], v[30:31], off
	global_store_dwordx4 v[228:229], v[52:55], off offset:512
	v_add_f32_e32 v29, v238, v239
	v_add_f32_e32 v28, v200, v28
	v_or_b32_e32 v30, 0x100, v226
	v_mov_b32_e32 v31, v227
	v_add_f32_e32 v40, v28, v29
	v_cvt_pk_bf16_f32 v28, v210, v211
	v_cvt_pk_bf16_f32 v29, v208, v209
	v_lshl_add_u64 v[30:31], s[12:13], 0, v[30:31]
	global_store_dwordx2 v[30:31], v[28:29], off
	v_pk_add_f32 v[30:31], v[198:199], v[62:63]
	v_pk_add_f32 v[28:29], v[196:197], v[60:61]
	v_mul_f32_e32 v42, v31, v31
	v_mul_f32_e32 v41, v29, v29
	v_fmac_f32_e32 v41, v28, v28
	v_fmac_f32_e32 v42, v30, v30
	v_add_f32_e32 v41, v41, v42
	v_add_f32_e32 v41, v40, v41
	ds_bpermute_b32 v42, v225, v41
	global_store_dwordx4 v[228:229], v[28:31], off offset:576
	v_or_b32_e32 v226, 0x120, v226
	s_nop 0
	v_pk_mul_f32 v[28:29], v[0:1], v[28:29]
	v_pk_mul_f32 v[30:31], v[2:3], v[30:31]
	v_cvt_pk_bf16_f32 v40, v28, v29
	s_waitcnt lgkmcnt(0)
	v_add_f32_e32 v28, v41, v42
	ds_bpermute_b32 v29, v224, v28
	v_cvt_pk_bf16_f32 v41, v30, v31
	v_lshl_add_u64 v[30:31], s[12:13], 0, v[226:227]
	global_store_dwordx2 v[30:31], v[40:41], off
	s_and_saveexec_b64 s[24:25], s[4:5]
	s_cbranch_execz .LBB0_234
	v_lshl_add_u64 v[30:31], v[64:65], 2, s[14:15]
	s_waitcnt lgkmcnt(0)
	v_add_f32_e32 v28, v28, v29
	v_mov_b32_e32 v242, v28
.LBB0_234:
	s_or_b64 exec, exec, s[24:25]
	v_or_b32_e32 v196, 48, v64
	v_ashrrev_i32_e32 v197, 31, v196
	v_readlane_b32 s60, v252, 0
	s_waitcnt lgkmcnt(0)
	v_lshlrev_b64 v[28:29], 13, v[196:197]
	v_readlane_b32 s61, v252, 1
	v_readlane_b32 s62, v252, 2
	v_readlane_b32 s63, v252, 3
	v_lshl_add_u64 v[28:29], s[60:61], 0, v[28:29]
	v_lshl_add_u64 v[28:29], v[140:141], 2, v[28:29]
	global_load_dwordx4 v[60:63], v[28:29], off
	global_load_dwordx4 v[52:55], v[28:29], off offset:64
	global_load_dwordx4 v[40:43], v[28:29], off offset:512
	s_nop 0
	global_load_dwordx4 v[28:31], v[28:29], off offset:576
	v_readlane_b32 s64, v252, 4
	v_readlane_b32 s65, v252, 5
	v_readlane_b32 s66, v252, 6
	v_readlane_b32 s67, v252, 7
	v_readlane_b32 s68, v252, 8
	v_readlane_b32 s69, v252, 9
	v_readlane_b32 s70, v252, 10
	v_readlane_b32 s71, v252, 11
	v_readlane_b32 s72, v252, 12
	v_readlane_b32 s73, v252, 13
	v_readlane_b32 s74, v252, 14
	v_readlane_b32 s75, v252, 15
	v_lshlrev_b64 v[198:199], 11, v[66:67]
	v_readlane_b32 s60, v252, 16
	v_lshl_add_u64 v[198:199], v[198:199], 0, v[140:141]
	v_pk_add_f32 v[58:59], v[194:195], v[58:59]
	v_pk_add_f32 v[56:57], v[192:193], v[56:57]
	v_readlane_b32 s74, v252, 30
	v_readlane_b32 s75, v252, 31
	v_mul_f32_e32 v65, v57, v57
	v_mul_f32_e32 v194, v59, v59
	v_lshl_add_u64 v[192:193], v[198:199], 2, s[74:75]
	global_store_dwordx4 v[192:193], v[56:59], off
	v_fmac_f32_e32 v65, v56, v56
	v_fmac_f32_e32 v194, v58, v58
	v_pk_mul_f32 v[58:59], v[14:15], v[58:59]
	v_pk_mul_f32 v[56:57], v[12:13], v[56:57]
	v_add_f32_e32 v65, v65, v194
	v_cvt_pk_bf16_f32 v56, v56, v57
	v_cvt_pk_bf16_f32 v57, v58, v59
	v_lshlrev_b64 v[58:59], 1, v[198:199]
	v_lshl_add_u64 v[194:195], s[12:13], 0, v[58:59]
	v_pk_add_f32 v[50:51], v[190:191], v[50:51]
	v_pk_add_f32 v[48:49], v[188:189], v[48:49]
	global_store_dwordx2 v[194:195], v[56:57], off
	v_mul_f32_e32 v56, v49, v49
	v_mul_f32_e32 v57, v51, v51
	global_store_dwordx4 v[192:193], v[48:51], off offset:64
	v_fmac_f32_e32 v56, v48, v48
	v_fmac_f32_e32 v57, v50, v50
	v_pk_mul_f32 v[50:51], v[10:11], v[50:51]
	v_pk_mul_f32 v[48:49], v[8:9], v[48:49]
	v_pk_add_f32 v[38:39], v[186:187], v[38:39]
	v_cvt_pk_bf16_f32 v48, v48, v49
	v_cvt_pk_bf16_f32 v49, v50, v51
	v_or_b32_e32 v50, 32, v58
	v_mov_b32_e32 v51, v59
	v_lshl_add_u64 v[50:51], s[12:13], 0, v[50:51]
	v_pk_add_f32 v[36:37], v[184:185], v[36:37]
	global_store_dwordx2 v[50:51], v[48:49], off
	v_mul_f32_e32 v48, v37, v37
	v_mul_f32_e32 v49, v39, v39
	global_store_dwordx4 v[192:193], v[36:39], off offset:512
	v_fmac_f32_e32 v48, v36, v36
	v_fmac_f32_e32 v49, v38, v38
	v_pk_mul_f32 v[38:39], v[6:7], v[38:39]
	v_pk_mul_f32 v[36:37], v[4:5], v[36:37]
	v_pk_add_f32 v[26:27], v[182:183], v[26:27]
	v_cvt_pk_bf16_f32 v36, v36, v37
	v_cvt_pk_bf16_f32 v37, v38, v39
	v_or_b32_e32 v38, 0x100, v58
	v_mov_b32_e32 v39, v59
	v_lshl_add_u64 v[38:39], s[12:13], 0, v[38:39]
	v_pk_add_f32 v[24:25], v[180:181], v[24:25]
	v_add_f32_e32 v56, v56, v57
	global_store_dwordx2 v[38:39], v[36:37], off
	v_mul_f32_e32 v36, v25, v25
	v_mul_f32_e32 v37, v27, v27
	v_add_f32_e32 v56, v65, v56
	v_add_f32_e32 v48, v48, v49
	v_fmac_f32_e32 v36, v24, v24
	v_fmac_f32_e32 v37, v26, v26
	v_add_f32_e32 v48, v56, v48
	v_add_f32_e32 v36, v36, v37
	v_add_f32_e32 v37, v48, v36
	ds_bpermute_b32 v38, v225, v37
	global_store_dwordx4 v[192:193], v[24:27], off offset:576
	v_or_b32_e32 v58, 0x120, v58
	v_readlane_b32 s61, v252, 17
	v_pk_mul_f32 v[24:25], v[0:1], v[24:25]
	v_pk_mul_f32 v[26:27], v[2:3], v[26:27]
	v_cvt_pk_bf16_f32 v36, v24, v25
	s_waitcnt lgkmcnt(0)
	v_add_f32_e32 v24, v37, v38
	ds_bpermute_b32 v25, v224, v24
	v_cvt_pk_bf16_f32 v37, v26, v27
	v_lshl_add_u64 v[26:27], s[12:13], 0, v[58:59]
	v_readlane_b32 s62, v252, 18
	v_readlane_b32 s63, v252, 19
	v_readlane_b32 s64, v252, 20
	v_readlane_b32 s65, v252, 21
	v_readlane_b32 s66, v252, 22
	v_readlane_b32 s67, v252, 23
	v_readlane_b32 s68, v252, 24
	v_readlane_b32 s69, v252, 25
	v_readlane_b32 s70, v252, 26
	v_readlane_b32 s71, v252, 27
	v_readlane_b32 s72, v252, 28
	v_readlane_b32 s73, v252, 29
	global_store_dwordx2 v[26:27], v[36:37], off
	s_and_saveexec_b64 s[24:25], s[4:5]
	s_cbranch_execz .LBB0_236
	v_lshl_add_u64 v[26:27], v[66:67], 2, s[14:15]
	s_waitcnt lgkmcnt(0)
	v_add_f32_e32 v24, v24, v25
	v_mov_b32_e32 v243, v24
.LBB0_236:
	s_or_b64 exec, exec, s[24:25]
	v_add_u32_e32 v180, 0x80, v64
	v_ashrrev_i32_e32 v181, 31, v180
	v_readlane_b32 s60, v252, 0
	s_waitcnt lgkmcnt(0)
	v_lshlrev_b64 v[24:25], 13, v[180:181]
	v_readlane_b32 s61, v252, 1
	v_readlane_b32 s62, v252, 2
	v_readlane_b32 s63, v252, 3
	v_lshl_add_u64 v[24:25], s[60:61], 0, v[24:25]
	v_lshl_add_u64 v[24:25], v[140:141], 2, v[24:25]
	global_load_dwordx4 v[64:67], v[24:25], off
	global_load_dwordx4 v[48:51], v[24:25], off offset:64
	global_load_dwordx4 v[36:39], v[24:25], off offset:512
	s_nop 0
	global_load_dwordx4 v[24:27], v[24:25], off offset:576
	v_readlane_b32 s64, v252, 4
	v_readlane_b32 s65, v252, 5
	v_readlane_b32 s66, v252, 6
	v_readlane_b32 s67, v252, 7
	v_readlane_b32 s68, v252, 8
	v_readlane_b32 s69, v252, 9
	v_readlane_b32 s70, v252, 10
	v_readlane_b32 s71, v252, 11
	v_readlane_b32 s72, v252, 12
	v_readlane_b32 s73, v252, 13
	v_readlane_b32 s74, v252, 14
	v_readlane_b32 s75, v252, 15
	v_lshlrev_b64 v[56:57], 11, v[214:215]
	v_readlane_b32 s60, v252, 16
	v_lshl_add_u64 v[56:57], v[56:57], 0, v[140:141]
	v_pk_add_f32 v[46:47], v[178:179], v[46:47]
	v_pk_add_f32 v[44:45], v[176:177], v[44:45]
	v_readlane_b32 s74, v252, 30
	v_readlane_b32 s75, v252, 31
	v_mul_f32_e32 v176, v45, v45
	v_mul_f32_e32 v177, v47, v47
	v_lshl_add_u64 v[58:59], v[56:57], 2, s[74:75]
	global_store_dwordx4 v[58:59], v[44:47], off
	v_fmac_f32_e32 v176, v44, v44
	v_fmac_f32_e32 v177, v46, v46
	v_pk_mul_f32 v[46:47], v[14:15], v[46:47]
	v_pk_mul_f32 v[44:45], v[12:13], v[44:45]
	v_pk_add_f32 v[34:35], v[174:175], v[34:35]
	v_cvt_pk_bf16_f32 v44, v44, v45
	v_cvt_pk_bf16_f32 v45, v46, v47
	v_lshlrev_b64 v[46:47], 1, v[56:57]
	v_lshl_add_u64 v[56:57], s[12:13], 0, v[46:47]
	v_pk_add_f32 v[32:33], v[172:173], v[32:33]
	global_store_dwordx2 v[56:57], v[44:45], off
	v_mul_f32_e32 v44, v33, v33
	v_mul_f32_e32 v45, v35, v35
	global_store_dwordx4 v[58:59], v[32:35], off offset:64
	v_fmac_f32_e32 v44, v32, v32
	v_fmac_f32_e32 v45, v34, v34
	v_pk_mul_f32 v[34:35], v[10:11], v[34:35]
	v_pk_mul_f32 v[32:33], v[8:9], v[32:33]
	v_pk_add_f32 v[22:23], v[170:171], v[22:23]
	v_cvt_pk_bf16_f32 v32, v32, v33
	v_cvt_pk_bf16_f32 v33, v34, v35
	v_or_b32_e32 v34, 32, v46
	v_mov_b32_e32 v35, v47
	v_lshl_add_u64 v[34:35], s[12:13], 0, v[34:35]
	v_pk_add_f32 v[20:21], v[168:169], v[20:21]
	global_store_dwordx2 v[34:35], v[32:33], off
	v_mul_f32_e32 v32, v21, v21
	v_mul_f32_e32 v33, v23, v23
	global_store_dwordx4 v[58:59], v[20:23], off offset:512
	v_fmac_f32_e32 v32, v20, v20
	v_fmac_f32_e32 v33, v22, v22
	v_pk_mul_f32 v[22:23], v[6:7], v[22:23]
	v_pk_mul_f32 v[20:21], v[4:5], v[20:21]
	v_pk_add_f32 v[18:19], v[166:167], v[18:19]
	v_cvt_pk_bf16_f32 v20, v20, v21
	v_cvt_pk_bf16_f32 v21, v22, v23
	v_or_b32_e32 v22, 0x100, v46
	v_mov_b32_e32 v23, v47
	v_lshl_add_u64 v[22:23], s[12:13], 0, v[22:23]
	v_pk_add_f32 v[16:17], v[164:165], v[16:17]
	v_add_f32_e32 v176, v176, v177
	v_add_f32_e32 v44, v44, v45
	global_store_dwordx2 v[22:23], v[20:21], off
	v_mul_f32_e32 v20, v17, v17
	v_mul_f32_e32 v21, v19, v19
	v_add_f32_e32 v44, v176, v44
	v_add_f32_e32 v32, v32, v33
	v_fmac_f32_e32 v20, v16, v16
	v_fmac_f32_e32 v21, v18, v18
	v_add_f32_e32 v32, v44, v32
	v_add_f32_e32 v20, v20, v21
	v_add_f32_e32 v21, v32, v20
	ds_bpermute_b32 v22, v225, v21
	global_store_dwordx4 v[58:59], v[16:19], off offset:576
	v_or_b32_e32 v46, 0x120, v46
	v_readlane_b32 s61, v252, 17
	v_pk_mul_f32 v[16:17], v[0:1], v[16:17]
	v_pk_mul_f32 v[18:19], v[2:3], v[18:19]
	v_cvt_pk_bf16_f32 v20, v16, v17
	s_waitcnt lgkmcnt(0)
	v_add_f32_e32 v16, v21, v22
	ds_bpermute_b32 v17, v224, v16
	v_cvt_pk_bf16_f32 v21, v18, v19
	v_lshl_add_u64 v[18:19], s[12:13], 0, v[46:47]
	v_readlane_b32 s62, v252, 18
	v_readlane_b32 s63, v252, 19
	v_readlane_b32 s64, v252, 20
	v_readlane_b32 s65, v252, 21
	v_readlane_b32 s66, v252, 22
	v_readlane_b32 s67, v252, 23
	v_readlane_b32 s68, v252, 24
	v_readlane_b32 s69, v252, 25
	v_readlane_b32 s70, v252, 26
	v_readlane_b32 s71, v252, 27
	v_readlane_b32 s72, v252, 28
	v_readlane_b32 s73, v252, 29
	global_store_dwordx2 v[18:19], v[20:21], off
	s_and_saveexec_b64 s[24:25], s[4:5]
	s_cbranch_execz .LBB0_238
	v_lshl_add_u64 v[18:19], v[214:215], 2, s[14:15]
	s_waitcnt lgkmcnt(0)
	v_add_f32_e32 v16, v16, v17
	v_mov_b32_e32 v244, v16
.LBB0_238:
	s_or_b64 exec, exec, s[24:25]
	s_waitcnt lgkmcnt(0)
	v_lshl_add_u64 v[16:17], v[140:141], 2, v[212:213]
	v_lshl_add_u64 v[18:19], v[16:17], 0, s[20:21]
	v_add_co_u32_e32 v16, vcc, 0x120000, v16
	v_lshlrev_b64 v[20:21], 11, v[196:197]
	s_nop 0
	v_addc_co_u32_e32 v17, vcc, 0, v17, vcc
	global_load_dwordx4 v[44:47], v[18:19], off offset:64
	global_load_dwordx4 v[32:35], v[18:19], off offset:512
	global_load_dwordx4 v[56:59], v[16:17], off
	s_nop 0
	global_load_dwordx4 v[16:19], v[18:19], off offset:576
	v_lshl_add_u64 v[164:165], v[20:21], 0, v[140:141]
	s_waitcnt vmcnt(25)
	v_pk_add_f32 v[22:23], v[160:161], v[62:63]
	v_pk_add_f32 v[20:21], v[158:159], v[60:61]
	v_readlane_b32 s60, v252, 16
	v_readlane_b32 s74, v252, 30
	v_readlane_b32 s75, v252, 31
	v_mul_f32_e32 v62, v21, v21
	v_mul_f32_e32 v63, v23, v23
	v_lshl_add_u64 v[60:61], v[164:165], 2, s[74:75]
	v_fmac_f32_e32 v62, v20, v20
	v_fmac_f32_e32 v63, v22, v22
	global_store_dwordx4 v[60:61], v[20:23], off
	v_add_f32_e32 v158, v62, v63
	v_lshlrev_b64 v[62:63], 1, v[164:165]
	v_pk_mul_f32 v[22:23], v[14:15], v[22:23]
	v_pk_mul_f32 v[20:21], v[12:13], v[20:21]
	v_readlane_b32 s61, v252, 17
	v_cvt_pk_bf16_f32 v20, v20, v21
	v_cvt_pk_bf16_f32 v21, v22, v23
	v_lshl_add_u64 v[22:23], s[12:13], 0, v[62:63]
	global_store_dwordx2 v[22:23], v[20:21], off
	s_waitcnt vmcnt(26)
	v_pk_add_f32 v[22:23], v[156:157], v[54:55]
	v_pk_add_f32 v[20:21], v[154:155], v[52:53]
	v_mul_f32_e32 v53, v23, v23
	v_mul_f32_e32 v52, v21, v21
	global_store_dwordx4 v[60:61], v[20:23], off offset:64
	v_fmac_f32_e32 v52, v20, v20
	v_fmac_f32_e32 v53, v22, v22
	v_pk_mul_f32 v[22:23], v[10:11], v[22:23]
	v_pk_mul_f32 v[20:21], v[8:9], v[20:21]
	v_add_f32_e32 v52, v52, v53
	v_cvt_pk_bf16_f32 v20, v20, v21
	v_cvt_pk_bf16_f32 v21, v22, v23
	v_or_b32_e32 v22, 32, v62
	v_mov_b32_e32 v23, v63
	v_lshl_add_u64 v[22:23], s[12:13], 0, v[22:23]
	global_store_dwordx2 v[22:23], v[20:21], off
	s_waitcnt vmcnt(27)
	v_pk_add_f32 v[22:23], v[152:153], v[42:43]
	v_pk_add_f32 v[20:21], v[150:151], v[40:41]
	v_mul_f32_e32 v41, v23, v23
	v_mul_f32_e32 v40, v21, v21
	global_store_dwordx4 v[60:61], v[20:23], off offset:512
	v_fmac_f32_e32 v40, v20, v20
	v_fmac_f32_e32 v41, v22, v22
	v_pk_mul_f32 v[22:23], v[6:7], v[22:23]
	v_pk_mul_f32 v[20:21], v[4:5], v[20:21]
	v_add_f32_e32 v52, v158, v52
	v_cvt_pk_bf16_f32 v20, v20, v21
	v_cvt_pk_bf16_f32 v21, v22, v23
	v_or_b32_e32 v22, 0x100, v62
	v_mov_b32_e32 v23, v63
	v_lshl_add_u64 v[22:23], s[12:13], 0, v[22:23]
	global_store_dwordx2 v[22:23], v[20:21], off
	s_waitcnt vmcnt(28)
	v_pk_add_f32 v[22:23], v[148:149], v[30:31]
	v_pk_add_f32 v[20:21], v[146:147], v[28:29]
	v_mul_f32_e32 v29, v23, v23
	v_mul_f32_e32 v28, v21, v21
	v_add_f32_e32 v40, v40, v41
	v_fmac_f32_e32 v28, v20, v20
	v_fmac_f32_e32 v29, v22, v22
	v_add_f32_e32 v40, v52, v40
	v_add_f32_e32 v28, v28, v29
	v_add_f32_e32 v29, v40, v28
	ds_bpermute_b32 v30, v225, v29
	global_store_dwordx4 v[60:61], v[20:23], off offset:576
	v_or_b32_e32 v62, 0x120, v62
	v_readlane_b32 s62, v252, 18
	v_pk_mul_f32 v[20:21], v[0:1], v[20:21]
	v_pk_mul_f32 v[22:23], v[2:3], v[22:23]
	v_cvt_pk_bf16_f32 v28, v20, v21
	s_waitcnt lgkmcnt(0)
	v_add_f32_e32 v20, v29, v30
	ds_bpermute_b32 v21, v224, v20
	v_cvt_pk_bf16_f32 v29, v22, v23
	v_lshl_add_u64 v[22:23], s[12:13], 0, v[62:63]
	v_readlane_b32 s63, v252, 19
	v_readlane_b32 s64, v252, 20
	v_readlane_b32 s65, v252, 21
	v_readlane_b32 s66, v252, 22
	v_readlane_b32 s67, v252, 23
	v_readlane_b32 s68, v252, 24
	v_readlane_b32 s69, v252, 25
	v_readlane_b32 s70, v252, 26
	v_readlane_b32 s71, v252, 27
	v_readlane_b32 s72, v252, 28
	v_readlane_b32 s73, v252, 29
	global_store_dwordx2 v[22:23], v[28:29], off
	s_and_saveexec_b64 s[24:25], s[4:5]
	s_cbranch_execz .LBB0_240
	v_lshl_add_u64 v[22:23], v[196:197], 2, s[14:15]
	s_waitcnt lgkmcnt(0)
	v_add_f32_e32 v20, v20, v21
	v_mov_b32_e32 v245, v20
.LBB0_240:
	s_or_b64 exec, exec, s[24:25]
	v_or_b32_e32 v146, 32, v180
	v_ashrrev_i32_e32 v147, 31, v146
	v_readlane_b32 s60, v252, 0
	s_waitcnt lgkmcnt(0)
	v_lshlrev_b64 v[20:21], 13, v[146:147]
	v_readlane_b32 s61, v252, 1
	v_readlane_b32 s62, v252, 2
	v_readlane_b32 s63, v252, 3
	v_lshl_add_u64 v[20:21], s[60:61], 0, v[20:21]
	v_lshl_add_u64 v[20:21], v[140:141], 2, v[20:21]
	global_load_dwordx4 v[52:55], v[20:21], off
	global_load_dwordx4 v[40:43], v[20:21], off offset:64
	global_load_dwordx4 v[28:31], v[20:21], off offset:512
	s_nop 0
	global_load_dwordx4 v[20:23], v[20:21], off offset:576
	v_readlane_b32 s64, v252, 4
	v_readlane_b32 s65, v252, 5
	v_readlane_b32 s66, v252, 6
	v_readlane_b32 s67, v252, 7
	v_readlane_b32 s68, v252, 8
	v_readlane_b32 s69, v252, 9
	v_readlane_b32 s70, v252, 10
	v_readlane_b32 s71, v252, 11
	v_readlane_b32 s72, v252, 12
	v_readlane_b32 s73, v252, 13
	v_readlane_b32 s74, v252, 14
	v_readlane_b32 s75, v252, 15
	v_lshlrev_b64 v[60:61], 11, v[180:181]
	v_readlane_b32 s60, v252, 16
	v_lshl_add_u64 v[148:149], v[60:61], 0, v[140:141]
	s_waitcnt vmcnt(25)
	v_pk_add_f32 v[62:63], v[144:145], v[66:67]
	v_pk_add_f32 v[60:61], v[142:143], v[64:65]
	v_readlane_b32 s74, v252, 30
	v_readlane_b32 s75, v252, 31
	v_mul_f32_e32 v66, v61, v61
	v_mul_f32_e32 v67, v63, v63
	v_lshl_add_u64 v[64:65], v[148:149], 2, s[74:75]
	global_store_dwordx4 v[64:65], v[60:63], off
	v_fmac_f32_e32 v66, v60, v60
	v_fmac_f32_e32 v67, v62, v62
	v_pk_mul_f32 v[62:63], v[14:15], v[62:63]
	v_pk_mul_f32 v[60:61], v[12:13], v[60:61]
	v_add_f32_e32 v142, v66, v67
	v_cvt_pk_bf16_f32 v60, v60, v61
	v_cvt_pk_bf16_f32 v61, v62, v63
	v_lshlrev_b64 v[62:63], 1, v[148:149]
	v_lshl_add_u64 v[66:67], s[12:13], 0, v[62:63]
	s_waitcnt vmcnt(25)
	v_pk_add_f32 v[50:51], v[126:127], v[50:51]
	v_pk_add_f32 v[48:49], v[124:125], v[48:49]
	global_store_dwordx2 v[66:67], v[60:61], off
	v_mul_f32_e32 v60, v49, v49
	v_mul_f32_e32 v61, v51, v51
	global_store_dwordx4 v[64:65], v[48:51], off offset:64
	v_fmac_f32_e32 v60, v48, v48
	v_fmac_f32_e32 v61, v50, v50
	v_pk_mul_f32 v[50:51], v[10:11], v[50:51]
	v_pk_mul_f32 v[48:49], v[8:9], v[48:49]
	s_waitcnt vmcnt(26)
	v_pk_add_f32 v[38:39], v[122:123], v[38:39]
	v_cvt_pk_bf16_f32 v48, v48, v49
	v_cvt_pk_bf16_f32 v49, v50, v51
	v_or_b32_e32 v50, 32, v62
	v_mov_b32_e32 v51, v63
	v_lshl_add_u64 v[50:51], s[12:13], 0, v[50:51]
	v_pk_add_f32 v[36:37], v[120:121], v[36:37]
	global_store_dwordx2 v[50:51], v[48:49], off
	v_mul_f32_e32 v48, v37, v37
	v_mul_f32_e32 v49, v39, v39
	global_store_dwordx4 v[64:65], v[36:39], off offset:512
	v_fmac_f32_e32 v48, v36, v36
	v_fmac_f32_e32 v49, v38, v38
	v_pk_mul_f32 v[38:39], v[6:7], v[38:39]
	v_pk_mul_f32 v[36:37], v[4:5], v[36:37]
	s_waitcnt vmcnt(27)
	v_pk_add_f32 v[26:27], v[118:119], v[26:27]
	v_cvt_pk_bf16_f32 v36, v36, v37
	v_cvt_pk_bf16_f32 v37, v38, v39
	v_or_b32_e32 v38, 0x100, v62
	v_mov_b32_e32 v39, v63
	v_lshl_add_u64 v[38:39], s[12:13], 0, v[38:39]
	v_pk_add_f32 v[24:25], v[116:117], v[24:25]
	v_add_f32_e32 v60, v60, v61
	global_store_dwordx2 v[38:39], v[36:37], off
	v_mul_f32_e32 v36, v25, v25
	v_mul_f32_e32 v37, v27, v27
	v_add_f32_e32 v60, v142, v60
	v_add_f32_e32 v48, v48, v49
	v_fmac_f32_e32 v36, v24, v24
	v_fmac_f32_e32 v37, v26, v26
	v_add_f32_e32 v48, v60, v48
	v_add_f32_e32 v36, v36, v37
	v_add_f32_e32 v37, v48, v36
	ds_bpermute_b32 v38, v225, v37
	global_store_dwordx4 v[64:65], v[24:27], off offset:576
	v_or_b32_e32 v62, 0x120, v62
	v_readlane_b32 s61, v252, 17
	v_pk_mul_f32 v[24:25], v[0:1], v[24:25]
	v_pk_mul_f32 v[26:27], v[2:3], v[26:27]
	v_cvt_pk_bf16_f32 v36, v24, v25
	s_waitcnt lgkmcnt(0)
	v_add_f32_e32 v24, v37, v38
	ds_bpermute_b32 v25, v224, v24
	v_cvt_pk_bf16_f32 v37, v26, v27
	v_lshl_add_u64 v[26:27], s[12:13], 0, v[62:63]
	v_readlane_b32 s62, v252, 18
	v_readlane_b32 s63, v252, 19
	v_readlane_b32 s64, v252, 20
	v_readlane_b32 s65, v252, 21
	v_readlane_b32 s66, v252, 22
	v_readlane_b32 s67, v252, 23
	v_readlane_b32 s68, v252, 24
	v_readlane_b32 s69, v252, 25
	v_readlane_b32 s70, v252, 26
	v_readlane_b32 s71, v252, 27
	v_readlane_b32 s72, v252, 28
	v_readlane_b32 s73, v252, 29
	global_store_dwordx2 v[26:27], v[36:37], off
	s_and_saveexec_b64 s[24:25], s[4:5]
	s_cbranch_execz .LBB0_242
	v_lshl_add_u64 v[26:27], v[180:181], 2, s[14:15]
	s_waitcnt lgkmcnt(0)
	v_add_f32_e32 v24, v24, v25
	v_mov_b32_e32 v246, v24
.LBB0_242:
	s_or_b64 exec, exec, s[24:25]
	v_or_b32_e32 v64, 48, v180
	v_ashrrev_i32_e32 v65, 31, v64
	v_readlane_b32 s60, v252, 0
	s_waitcnt lgkmcnt(0)
	v_lshlrev_b64 v[24:25], 13, v[64:65]
	v_readlane_b32 s61, v252, 1
	v_or_b32_e32 v66, 16, v180
	v_readlane_b32 s62, v252, 2
	v_lshl_add_u64 v[24:25], s[60:61], 0, v[24:25]
	v_lshl_add_u64 v[24:25], v[140:141], 2, v[24:25]
	global_load_dwordx4 v[60:63], v[24:25], off
	global_load_dwordx4 v[48:51], v[24:25], off offset:64
	global_load_dwordx4 v[36:39], v[24:25], off offset:512
	s_nop 0
	global_load_dwordx4 v[24:27], v[24:25], off offset:576
	v_readlane_b32 s63, v252, 3
	v_readlane_b32 s64, v252, 4
	v_readlane_b32 s65, v252, 5
	v_readlane_b32 s66, v252, 6
	v_readlane_b32 s67, v252, 7
	v_readlane_b32 s68, v252, 8
	v_readlane_b32 s69, v252, 9
	v_readlane_b32 s70, v252, 10
	v_readlane_b32 s71, v252, 11
	v_readlane_b32 s72, v252, 12
	v_readlane_b32 s73, v252, 13
	v_readlane_b32 s74, v252, 14
	v_readlane_b32 s75, v252, 15
	v_ashrrev_i32_e32 v67, 31, v66
	v_lshlrev_b64 v[116:117], 11, v[66:67]
	v_readlane_b32 s60, v252, 16
	v_lshl_add_u64 v[116:117], v[116:117], 0, v[140:141]
	s_waitcnt vmcnt(23)
	v_pk_add_f32 v[58:59], v[114:115], v[58:59]
	v_pk_add_f32 v[56:57], v[112:113], v[56:57]
	v_readlane_b32 s74, v252, 30
	v_readlane_b32 s75, v252, 31
	v_mul_f32_e32 v114, v57, v57
	v_mul_f32_e32 v115, v59, v59
	v_lshl_add_u64 v[112:113], v[116:117], 2, s[74:75]
	global_store_dwordx4 v[112:113], v[56:59], off
	v_fmac_f32_e32 v114, v56, v56
	v_fmac_f32_e32 v115, v58, v58
	v_pk_mul_f32 v[58:59], v[14:15], v[58:59]
	v_pk_mul_f32 v[56:57], v[12:13], v[56:57]
	v_add_f32_e32 v118, v114, v115
	v_cvt_pk_bf16_f32 v56, v56, v57
	v_cvt_pk_bf16_f32 v57, v58, v59
	v_lshlrev_b64 v[58:59], 1, v[116:117]
	v_lshl_add_u64 v[114:115], s[12:13], 0, v[58:59]
	v_pk_add_f32 v[46:47], v[110:111], v[46:47]
	v_pk_add_f32 v[44:45], v[108:109], v[44:45]
	global_store_dwordx2 v[114:115], v[56:57], off
	v_mul_f32_e32 v56, v45, v45
	v_mul_f32_e32 v57, v47, v47
	global_store_dwordx4 v[112:113], v[44:47], off offset:64
	v_fmac_f32_e32 v56, v44, v44
	v_fmac_f32_e32 v57, v46, v46
	v_pk_mul_f32 v[46:47], v[10:11], v[46:47]
	v_pk_mul_f32 v[44:45], v[8:9], v[44:45]
	v_pk_add_f32 v[34:35], v[106:107], v[34:35]
	v_cvt_pk_bf16_f32 v44, v44, v45
	v_cvt_pk_bf16_f32 v45, v46, v47
	v_or_b32_e32 v46, 32, v58
	v_mov_b32_e32 v47, v59
	v_lshl_add_u64 v[46:47], s[12:13], 0, v[46:47]
	v_pk_add_f32 v[32:33], v[104:105], v[32:33]
	global_store_dwordx2 v[46:47], v[44:45], off
	v_mul_f32_e32 v44, v33, v33
	v_mul_f32_e32 v45, v35, v35
	global_store_dwordx4 v[112:113], v[32:35], off offset:512
	v_fmac_f32_e32 v44, v32, v32
	v_fmac_f32_e32 v45, v34, v34
	v_pk_mul_f32 v[34:35], v[6:7], v[34:35]
	v_pk_mul_f32 v[32:33], v[4:5], v[32:33]
	s_waitcnt vmcnt(27)
	v_pk_add_f32 v[18:19], v[102:103], v[18:19]
	v_cvt_pk_bf16_f32 v32, v32, v33
	v_cvt_pk_bf16_f32 v33, v34, v35
	v_or_b32_e32 v34, 0x100, v58
	v_mov_b32_e32 v35, v59
	v_lshl_add_u64 v[34:35], s[12:13], 0, v[34:35]
	v_pk_add_f32 v[16:17], v[100:101], v[16:17]
	v_add_f32_e32 v56, v56, v57
	global_store_dwordx2 v[34:35], v[32:33], off
	v_mul_f32_e32 v32, v17, v17
	v_mul_f32_e32 v33, v19, v19
	v_add_f32_e32 v56, v118, v56
	v_add_f32_e32 v44, v44, v45
	v_fmac_f32_e32 v32, v16, v16
	v_fmac_f32_e32 v33, v18, v18
	v_add_f32_e32 v44, v56, v44
	v_add_f32_e32 v32, v32, v33
	v_add_f32_e32 v33, v44, v32
	ds_bpermute_b32 v34, v225, v33
	global_store_dwordx4 v[112:113], v[16:19], off offset:576
	v_or_b32_e32 v58, 0x120, v58
	v_readlane_b32 s61, v252, 17
	v_pk_mul_f32 v[16:17], v[0:1], v[16:17]
	v_pk_mul_f32 v[18:19], v[2:3], v[18:19]
	v_cvt_pk_bf16_f32 v32, v16, v17
	s_waitcnt lgkmcnt(0)
	v_add_f32_e32 v16, v33, v34
	ds_bpermute_b32 v17, v224, v16
	v_cvt_pk_bf16_f32 v33, v18, v19
	v_lshl_add_u64 v[18:19], s[12:13], 0, v[58:59]
	v_readlane_b32 s62, v252, 18
	v_readlane_b32 s63, v252, 19
	v_readlane_b32 s64, v252, 20
	v_readlane_b32 s65, v252, 21
	v_readlane_b32 s66, v252, 22
	v_readlane_b32 s67, v252, 23
	v_readlane_b32 s68, v252, 24
	v_readlane_b32 s69, v252, 25
	v_readlane_b32 s70, v252, 26
	v_readlane_b32 s71, v252, 27
	v_readlane_b32 s72, v252, 28
	v_readlane_b32 s73, v252, 29
	global_store_dwordx2 v[18:19], v[32:33], off
	s_and_saveexec_b64 s[24:25], s[4:5]
	s_cbranch_execz .LBB0_244
	v_lshl_add_u64 v[18:19], v[66:67], 2, s[14:15]
	s_waitcnt lgkmcnt(0)
	v_add_f32_e32 v16, v16, v17
	v_mov_b32_e32 v247, v16
.LBB0_244:
	s_or_b64 exec, exec, s[24:25]
	s_waitcnt lgkmcnt(0)
	v_lshlrev_b64 v[16:17], 11, v[146:147]
	v_readlane_b32 s60, v252, 16
	v_lshl_add_u64 v[32:33], v[16:17], 0, v[140:141]
	s_waitcnt vmcnt(21)
	v_pk_add_f32 v[18:19], v[98:99], v[54:55]
	v_pk_add_f32 v[16:17], v[96:97], v[52:53]
	v_readlane_b32 s74, v252, 30
	v_readlane_b32 s75, v252, 31
	v_mul_f32_e32 v44, v17, v17
	v_mul_f32_e32 v45, v19, v19
	v_lshl_add_u64 v[34:35], v[32:33], 2, s[74:75]
	global_store_dwordx4 v[34:35], v[16:19], off
	v_fmac_f32_e32 v44, v16, v16
	v_fmac_f32_e32 v45, v18, v18
	v_pk_mul_f32 v[18:19], v[14:15], v[18:19]
	v_pk_mul_f32 v[16:17], v[12:13], v[16:17]
	v_lshlrev_b64 v[32:33], 1, v[32:33]
	v_cvt_pk_bf16_f32 v16, v16, v17
	v_cvt_pk_bf16_f32 v17, v18, v19
	v_lshl_add_u64 v[18:19], s[12:13], 0, v[32:33]
	global_store_dwordx2 v[18:19], v[16:17], off
	s_waitcnt vmcnt(22)
	v_pk_add_f32 v[18:19], v[94:95], v[42:43]
	v_pk_add_f32 v[16:17], v[92:93], v[40:41]
	v_mul_f32_e32 v41, v19, v19
	v_mul_f32_e32 v40, v17, v17
	global_store_dwordx4 v[34:35], v[16:19], off offset:64
	v_fmac_f32_e32 v40, v16, v16
	v_fmac_f32_e32 v41, v18, v18
	v_pk_mul_f32 v[18:19], v[10:11], v[18:19]
	v_pk_mul_f32 v[16:17], v[8:9], v[16:17]
	v_add_f32_e32 v44, v44, v45
	v_cvt_pk_bf16_f32 v16, v16, v17
	v_cvt_pk_bf16_f32 v17, v18, v19
	v_or_b32_e32 v18, 32, v32
	v_mov_b32_e32 v19, v33
	v_lshl_add_u64 v[18:19], s[12:13], 0, v[18:19]
	global_store_dwordx2 v[18:19], v[16:17], off
	s_waitcnt vmcnt(23)
	v_pk_add_f32 v[18:19], v[90:91], v[30:31]
	v_pk_add_f32 v[16:17], v[88:89], v[28:29]
	v_mul_f32_e32 v29, v19, v19
	v_mul_f32_e32 v28, v17, v17
	global_store_dwordx4 v[34:35], v[16:19], off offset:512
	v_fmac_f32_e32 v28, v16, v16
	v_fmac_f32_e32 v29, v18, v18
	v_pk_mul_f32 v[18:19], v[6:7], v[18:19]
	v_pk_mul_f32 v[16:17], v[4:5], v[16:17]
	v_add_f32_e32 v40, v40, v41
	v_cvt_pk_bf16_f32 v16, v16, v17
	v_cvt_pk_bf16_f32 v17, v18, v19
	v_or_b32_e32 v18, 0x100, v32
	v_mov_b32_e32 v19, v33
	v_lshl_add_u64 v[18:19], s[12:13], 0, v[18:19]
	global_store_dwordx2 v[18:19], v[16:17], off
	s_waitcnt vmcnt(24)
	v_pk_add_f32 v[18:19], v[86:87], v[22:23]
	v_pk_add_f32 v[16:17], v[84:85], v[20:21]
	v_mul_f32_e32 v21, v19, v19
	v_mul_f32_e32 v20, v17, v17
	v_add_f32_e32 v40, v44, v40
	v_add_f32_e32 v28, v28, v29
	v_fmac_f32_e32 v20, v16, v16
	v_fmac_f32_e32 v21, v18, v18
	v_add_f32_e32 v28, v40, v28
	v_add_f32_e32 v20, v20, v21
	v_add_f32_e32 v21, v28, v20
	ds_bpermute_b32 v22, v225, v21
	global_store_dwordx4 v[34:35], v[16:19], off offset:576
	v_or_b32_e32 v32, 0x120, v32
	v_readlane_b32 s61, v252, 17
	v_pk_mul_f32 v[16:17], v[0:1], v[16:17]
	v_pk_mul_f32 v[18:19], v[2:3], v[18:19]
	v_cvt_pk_bf16_f32 v20, v16, v17
	s_waitcnt lgkmcnt(0)
	v_add_f32_e32 v16, v21, v22
	ds_bpermute_b32 v17, v224, v16
	v_cvt_pk_bf16_f32 v21, v18, v19
	v_lshl_add_u64 v[18:19], s[12:13], 0, v[32:33]
	v_readlane_b32 s62, v252, 18
	v_readlane_b32 s63, v252, 19
	v_readlane_b32 s64, v252, 20
	v_readlane_b32 s65, v252, 21
	v_readlane_b32 s66, v252, 22
	v_readlane_b32 s67, v252, 23
	v_readlane_b32 s68, v252, 24
	v_readlane_b32 s69, v252, 25
	v_readlane_b32 s70, v252, 26
	v_readlane_b32 s71, v252, 27
	v_readlane_b32 s72, v252, 28
	v_readlane_b32 s73, v252, 29
	global_store_dwordx2 v[18:19], v[20:21], off
	s_and_saveexec_b64 s[24:25], s[4:5]
	s_cbranch_execz .LBB0_246
	v_lshl_add_u64 v[18:19], v[146:147], 2, s[14:15]
	s_waitcnt lgkmcnt(0)
	v_add_f32_e32 v16, v16, v17
	v_mov_b32_e32 v248, v16
.LBB0_246:
	s_or_b64 exec, exec, s[24:25]
	s_waitcnt lgkmcnt(0)
	v_lshlrev_b64 v[16:17], 11, v[64:65]
	v_readlane_b32 s60, v252, 16
	v_lshl_add_u64 v[20:21], v[16:17], 0, v[140:141]
	s_waitcnt vmcnt(17)
	v_pk_add_f32 v[16:17], v[80:81], v[60:61]
	v_readlane_b32 s74, v252, 30
	v_readlane_b32 s75, v252, 31
	v_pk_add_f32 v[18:19], v[82:83], v[62:63]
	v_mul_f32_e32 v28, v17, v17
	v_lshl_add_u64 v[22:23], v[20:21], 2, s[74:75]
	global_store_dwordx4 v[22:23], v[16:19], off
	v_fmac_f32_e32 v28, v16, v16
	v_pk_mul_f32 v[14:15], v[14:15], v[18:19]
	v_pk_mul_f32 v[12:13], v[12:13], v[16:17]
	v_lshlrev_b64 v[16:17], 1, v[20:21]
	v_cvt_pk_bf16_f32 v12, v12, v13
	v_cvt_pk_bf16_f32 v13, v14, v15
	v_lshl_add_u64 v[14:15], s[12:13], 0, v[16:17]
	global_store_dwordx2 v[14:15], v[12:13], off
	s_waitcnt vmcnt(18)
	v_pk_add_f32 v[14:15], v[78:79], v[50:51]
	v_pk_add_f32 v[12:13], v[76:77], v[48:49]
	v_pk_mul_f32 v[10:11], v[10:11], v[14:15]
	v_pk_mul_f32 v[8:9], v[8:9], v[12:13]
	global_store_dwordx4 v[22:23], v[12:15], off offset:64
	v_cvt_pk_bf16_f32 v8, v8, v9
	v_cvt_pk_bf16_f32 v9, v10, v11
	v_or_b32_e32 v10, 32, v16
	v_mov_b32_e32 v11, v17
	v_lshl_add_u64 v[10:11], s[12:13], 0, v[10:11]
	global_store_dwordx2 v[10:11], v[8:9], off
	s_waitcnt vmcnt(19)
	v_pk_add_f32 v[10:11], v[74:75], v[38:39]
	v_pk_add_f32 v[8:9], v[72:73], v[36:37]
	v_pk_mul_f32 v[6:7], v[6:7], v[10:11]
	v_pk_mul_f32 v[4:5], v[4:5], v[8:9]
	v_mul_f32_e32 v29, v19, v19
	v_cvt_pk_bf16_f32 v4, v4, v5
	v_cvt_pk_bf16_f32 v5, v6, v7
	v_or_b32_e32 v6, 0x100, v16
	v_mov_b32_e32 v7, v17
	v_fmac_f32_e32 v29, v18, v18
	v_mul_f32_e32 v18, v13, v13
	v_mul_f32_e32 v19, v15, v15
	v_lshl_add_u64 v[6:7], s[12:13], 0, v[6:7]
	v_fmac_f32_e32 v18, v12, v12
	v_fmac_f32_e32 v19, v14, v14
	global_store_dwordx4 v[22:23], v[8:11], off offset:512
	v_mul_f32_e32 v12, v9, v9
	v_mul_f32_e32 v13, v11, v11
	global_store_dwordx2 v[6:7], v[4:5], off
	s_waitcnt vmcnt(20)
	v_pk_add_f32 v[6:7], v[70:71], v[26:27]
	v_pk_add_f32 v[4:5], v[68:69], v[24:25]
	v_add_f32_e32 v28, v28, v29
	v_add_f32_e32 v18, v18, v19
	v_fmac_f32_e32 v12, v8, v8
	v_fmac_f32_e32 v13, v10, v10
	v_mul_f32_e32 v8, v5, v5
	v_mul_f32_e32 v9, v7, v7
	v_add_f32_e32 v18, v28, v18
	v_add_f32_e32 v12, v12, v13
	v_fmac_f32_e32 v8, v4, v4
	v_fmac_f32_e32 v9, v6, v6
	v_add_f32_e32 v12, v18, v12
	v_add_f32_e32 v8, v8, v9
	v_add_f32_e32 v8, v12, v8
	ds_bpermute_b32 v9, v225, v8
	v_pk_mul_f32 v[0:1], v[0:1], v[4:5]
	global_store_dwordx4 v[22:23], v[4:7], off offset:576
	v_pk_mul_f32 v[2:3], v[2:3], v[6:7]
	v_or_b32_e32 v16, 0x120, v16
	v_cvt_pk_bf16_f32 v4, v0, v1
	s_waitcnt lgkmcnt(0)
	v_add_f32_e32 v0, v8, v9
	ds_bpermute_b32 v1, v224, v0
	v_cvt_pk_bf16_f32 v5, v2, v3
	v_lshl_add_u64 v[2:3], s[12:13], 0, v[16:17]
	v_readlane_b32 s61, v252, 17
	v_readlane_b32 s62, v252, 18
	v_readlane_b32 s63, v252, 19
	v_readlane_b32 s64, v252, 20
	v_readlane_b32 s65, v252, 21
	v_readlane_b32 s66, v252, 22
	v_readlane_b32 s67, v252, 23
	v_readlane_b32 s68, v252, 24
	v_readlane_b32 s69, v252, 25
	v_readlane_b32 s70, v252, 26
	v_readlane_b32 s71, v252, 27
	v_readlane_b32 s72, v252, 28
	v_readlane_b32 s73, v252, 29
	global_store_dwordx2 v[2:3], v[4:5], off
	s_and_saveexec_b64 s[24:25], s[4:5]
	s_cbranch_execz .LBB0_248
	v_lshl_add_u64 v[2:3], v[64:65], 2, s[14:15]
	s_waitcnt lgkmcnt(0)
	v_add_f32_e32 v0, v0, v1
	global_atomic_add_f32 v[2:3], v0, off
	global_atomic_add_f32 v[2:3], v242, off offset:-704
	global_atomic_add_f32 v[2:3], v243, off offset:-640
	global_atomic_add_f32 v[2:3], v244, off offset:-576
	global_atomic_add_f32 v[2:3], v245, off offset:-512
	global_atomic_add_f32 v[2:3], v246, off offset:-192
	global_atomic_add_f32 v[2:3], v247, off offset:-128
	global_atomic_add_f32 v[2:3], v248, off offset:-64

.LBB0_852:
	v_lshl_add_u32 v200, s54, 8, v206
	v_readlane_b32 s60, v252, 16
	v_lshl_or_b32 v188, s55, 8, v208
	v_ashrrev_i32_e32 v201, 31, v200
	v_readlane_b32 s74, v252, 30
	v_readlane_b32 s75, v252, 31
	v_ashrrev_i32_e32 v189, 31, v188
	v_lshlrev_b64 v[112:113], 13, v[200:201]
	v_readlane_b32 s72, v252, 28
	v_readlane_b32 s73, v252, 29
	s_mov_b64 s[82:83], s[74:75]
	v_lshlrev_b64 v[144:145], 2, v[188:189]
	v_readlane_b32 s61, v252, 17
	v_readlane_b32 s62, v252, 18
	v_readlane_b32 s63, v252, 19
	v_readlane_b32 s64, v252, 20
	v_readlane_b32 s65, v252, 21
	v_readlane_b32 s66, v252, 22
	v_readlane_b32 s67, v252, 23
	v_readlane_b32 s68, v252, 24
	v_readlane_b32 s69, v252, 25
	v_readlane_b32 s70, v252, 26
	v_readlane_b32 s71, v252, 27
	v_lshl_add_u64 v[190:191], s[82:83], 0, v[112:113]
	s_mov_b64 s[80:81], s[72:73]
	v_lshl_add_u64 v[230:231], v[190:191], 0, v[144:145]
	v_readlane_b32 s60, v252, 32
	global_load_dwordx4 v[196:199], v[230:231], off
	global_load_dwordx4 v[216:219], v[230:231], off offset:64
	global_load_dwordx4 v[222:225], v[230:231], off offset:512
	v_readlane_b32 s74, v252, 46
	v_readlane_b32 s75, v252, 47
	v_or_b32_e32 v202, 16, v200
	v_or_b32_e32 v192, 32, v200
	v_lshl_add_u64 v[112:113], s[74:75], 0, v[144:145]
	global_load_dwordx4 v[128:131], v[112:113], off
	global_load_dwordx4 v[120:123], v[112:113], off offset:64
	global_load_dwordx4 v[116:119], v[112:113], off offset:512
	global_load_dwordx4 v[226:229], v[230:231], off offset:576
	v_ashrrev_i32_e32 v203, 31, v202
	v_ashrrev_i32_e32 v193, 31, v192
	v_lshlrev_b64 v[146:147], 13, v[202:203]
	v_lshlrev_b64 v[148:149], 13, v[192:193]
	v_lshl_add_u64 v[146:147], s[82:83], 0, v[146:147]
	global_load_dwordx4 v[112:115], v[112:113], off offset:576
	v_lshl_add_u64 v[148:149], s[82:83], 0, v[148:149]
	v_lshl_add_u64 v[204:205], v[146:147], 0, v[144:145]
	v_lshl_add_u64 v[194:195], v[148:149], 0, v[144:145]
	global_load_dwordx4 v[172:175], v[204:205], off
	global_load_dwordx4 v[168:171], v[204:205], off offset:64
	global_load_dwordx4 v[164:167], v[204:205], off offset:512
	global_load_dwordx4 v[160:163], v[204:205], off offset:576
	global_load_dwordx4 v[156:159], v[194:195], off
	global_load_dwordx4 v[152:155], v[194:195], off offset:64
	global_load_dwordx4 v[148:151], v[194:195], off offset:512
	global_load_dwordx4 v[144:147], v[194:195], off offset:576
	v_and_b32_e32 v214, 64, v212
	v_xor_b32_e32 v213, 16, v212
	v_add_u32_e32 v214, 64, v214
	v_xor_b32_e32 v215, 32, v212
	v_cmp_lt_i32_e32 vcc, v213, v214
	v_lshlrev_b64 v[232:233], 11, v[200:201]
	v_lshl_add_u64 v[232:233], v[232:233], 0, v[188:189]
	v_cndmask_b32_e32 v213, v212, v213, vcc
	v_cmp_lt_i32_e32 vcc, v215, v214
	v_lshlrev_b32_e32 v214, 2, v213
	v_lshlrev_b64 v[232:233], 1, v[232:233]
	v_cndmask_b32_e32 v215, v212, v215, vcc
	v_lshlrev_b32_e32 v213, 2, v215
	v_lshl_add_u64 v[234:235], s[14:15], 0, v[232:233]
	v_or_b32_e32 v236, 32, v232
	v_mov_b32_e32 v237, v233
	v_lshl_add_u64 v[236:237], s[14:15], 0, v[236:237]
	v_readlane_b32 s61, v252, 33
	v_readlane_b32 s62, v252, 34
	v_readlane_b32 s63, v252, 35
	v_readlane_b32 s64, v252, 36
	v_readlane_b32 s65, v252, 37
	v_readlane_b32 s66, v252, 38
	v_readlane_b32 s67, v252, 39
	v_readlane_b32 s68, v252, 40
	v_readlane_b32 s69, v252, 41
	v_readlane_b32 s70, v252, 42
	v_readlane_b32 s71, v252, 43
	v_readlane_b32 s72, v252, 44
	v_readlane_b32 s73, v252, 45
	s_waitcnt vmcnt(0)
	v_pk_add_f32 v[138:139], v[138:139], v[198:199]
	v_pk_add_f32 v[136:137], v[136:137], v[196:197]
	v_pk_add_f32 v[142:143], v[142:143], v[218:219]
	v_pk_add_f32 v[140:141], v[140:141], v[216:217]
	v_pk_add_f32 v[134:135], v[134:135], v[224:225]
	v_pk_add_f32 v[132:133], v[132:133], v[222:223]
	v_mul_f32_e32 v215, v137, v137
	v_mul_f32_e32 v221, v139, v139
	v_pk_mul_f32 v[196:197], v[130:131], v[138:139]
	v_pk_mul_f32 v[198:199], v[128:129], v[136:137]
	v_mul_f32_e32 v238, v141, v141
	v_mul_f32_e32 v239, v143, v143
	global_store_dwordx4 v[230:231], v[136:139], off
	v_pk_mul_f32 v[216:217], v[122:123], v[142:143]
	v_pk_mul_f32 v[218:219], v[120:121], v[140:141]
	v_mul_f32_e32 v240, v133, v133
	v_mul_f32_e32 v241, v135, v135
	v_fmac_f32_e32 v215, v136, v136
	v_fmac_f32_e32 v221, v138, v138
	v_cvt_pk_bf16_f32 v136, v198, v199
	v_cvt_pk_bf16_f32 v137, v196, v197
	v_fmac_f32_e32 v238, v140, v140
	v_fmac_f32_e32 v239, v142, v142
	v_cvt_pk_bf16_f32 v138, v218, v219
	v_cvt_pk_bf16_f32 v139, v216, v217
	v_fmac_f32_e32 v240, v132, v132
	v_fmac_f32_e32 v241, v134, v134
	v_add_f32_e32 v197, v215, v221
	global_store_dwordx2 v[234:235], v[136:137], off
	global_store_dwordx4 v[230:231], v[140:143], off offset:64
	v_add_f32_e32 v136, v238, v239
	v_pk_mul_f32 v[224:225], v[116:117], v[132:133]
	global_store_dwordx2 v[236:237], v[138:139], off
	global_store_dwordx4 v[230:231], v[132:135], off offset:512
	v_pk_mul_f32 v[222:223], v[118:119], v[134:135]
	v_cvt_pk_bf16_f32 v196, v224, v225
	v_add_f32_e32 v132, v240, v241
	v_add_f32_e32 v133, v197, v136
	v_add_f32_e32 v134, v133, v132
	v_or_b32_e32 v132, 0x100, v232
	v_mov_b32_e32 v133, v233
	v_cvt_pk_bf16_f32 v197, v222, v223
	v_lshl_add_u64 v[132:133], s[14:15], 0, v[132:133]
	v_pk_add_f32 v[126:127], v[126:127], v[228:229]
	v_pk_add_f32 v[124:125], v[124:125], v[226:227]
	global_store_dwordx2 v[132:133], v[196:197], off
	v_mul_f32_e32 v132, v125, v125
	v_mul_f32_e32 v133, v127, v127
	v_fmac_f32_e32 v132, v124, v124
	v_fmac_f32_e32 v133, v126, v126
	v_add_f32_e32 v132, v132, v133
	v_add_f32_e32 v133, v134, v132
	ds_bpermute_b32 v134, v214, v133
	global_store_dwordx4 v[230:231], v[124:127], off offset:576
	v_or_b32_e32 v232, 0x120, v232
	s_nop 0
	v_pk_mul_f32 v[124:125], v[112:113], v[124:125]
	v_pk_mul_f32 v[126:127], v[114:115], v[126:127]
	v_cvt_pk_bf16_f32 v132, v124, v125
	s_waitcnt lgkmcnt(0)
	v_add_f32_e32 v124, v133, v134
	ds_bpermute_b32 v125, v213, v124
	v_cvt_pk_bf16_f32 v133, v126, v127
	v_lshl_add_u64 v[126:127], s[14:15], 0, v[232:233]
	global_store_dwordx2 v[126:127], v[132:133], off
	s_and_saveexec_b64 s[28:29], s[2:3]
	s_cbranch_execz .LBB0_854
	v_lshl_add_u64 v[126:127], v[200:201], 2, s[16:17]
	s_waitcnt lgkmcnt(0)
	v_add_f32_e32 v124, v124, v125
	v_mov_b32_e32 v242, v124
.LBB0_854:
	s_or_b64 exec, exec, s[28:29]
	v_or_b32_e32 v196, 48, v200
	v_ashrrev_i32_e32 v197, 31, v196
	v_readlane_b32 s60, v252, 16
	s_waitcnt lgkmcnt(0)
	v_lshlrev_b64 v[124:125], 13, v[196:197]
	v_readlane_b32 s74, v252, 30
	v_readlane_b32 s75, v252, 31
	v_pk_add_f32 v[110:111], v[110:111], v[174:175]
	v_pk_add_f32 v[108:109], v[108:109], v[172:173]
	v_lshl_add_u64 v[124:125], s[74:75], 0, v[124:125]
	v_lshl_add_u64 v[198:199], v[188:189], 2, v[124:125]
	global_load_dwordx4 v[140:143], v[198:199], off
	global_load_dwordx4 v[136:139], v[198:199], off offset:64
	global_load_dwordx4 v[132:135], v[198:199], off offset:512
	global_load_dwordx4 v[124:127], v[198:199], off offset:576
	v_lshlrev_b64 v[216:217], 11, v[202:203]
	v_mul_f32_e32 v172, v109, v109
	v_mul_f32_e32 v173, v111, v111
	v_lshl_add_u64 v[216:217], v[216:217], 0, v[188:189]
	global_store_dwordx4 v[204:205], v[108:111], off
	v_fmac_f32_e32 v172, v108, v108
	v_fmac_f32_e32 v173, v110, v110
	v_pk_mul_f32 v[110:111], v[130:131], v[110:111]
	v_pk_mul_f32 v[108:109], v[128:129], v[108:109]
	v_add_f32_e32 v174, v172, v173
	v_cvt_pk_bf16_f32 v108, v108, v109
	v_cvt_pk_bf16_f32 v109, v110, v111
	v_lshlrev_b64 v[110:111], 1, v[216:217]
	v_lshl_add_u64 v[172:173], s[14:15], 0, v[110:111]
	v_pk_add_f32 v[106:107], v[106:107], v[170:171]
	v_pk_add_f32 v[104:105], v[104:105], v[168:169]
	global_store_dwordx2 v[172:173], v[108:109], off
	v_mul_f32_e32 v108, v105, v105
	v_mul_f32_e32 v109, v107, v107
	global_store_dwordx4 v[204:205], v[104:107], off offset:64
	v_fmac_f32_e32 v108, v104, v104
	v_fmac_f32_e32 v109, v106, v106
	v_pk_mul_f32 v[106:107], v[122:123], v[106:107]
	v_pk_mul_f32 v[104:105], v[120:121], v[104:105]
	v_pk_add_f32 v[102:103], v[102:103], v[166:167]
	v_cvt_pk_bf16_f32 v104, v104, v105
	v_cvt_pk_bf16_f32 v105, v106, v107
	v_or_b32_e32 v106, 32, v110
	v_mov_b32_e32 v107, v111
	v_lshl_add_u64 v[106:107], s[14:15], 0, v[106:107]
	v_pk_add_f32 v[100:101], v[100:101], v[164:165]
	global_store_dwordx2 v[106:107], v[104:105], off
	v_mul_f32_e32 v104, v101, v101
	v_mul_f32_e32 v105, v103, v103
	global_store_dwordx4 v[204:205], v[100:103], off offset:512
	v_fmac_f32_e32 v104, v100, v100
	v_fmac_f32_e32 v105, v102, v102
	v_pk_mul_f32 v[102:103], v[118:119], v[102:103]
	v_pk_mul_f32 v[100:101], v[116:117], v[100:101]
	v_pk_add_f32 v[98:99], v[98:99], v[162:163]
	v_cvt_pk_bf16_f32 v100, v100, v101
	v_cvt_pk_bf16_f32 v101, v102, v103
	v_or_b32_e32 v102, 0x100, v110
	v_mov_b32_e32 v103, v111
	v_lshl_add_u64 v[102:103], s[14:15], 0, v[102:103]
	v_pk_add_f32 v[96:97], v[96:97], v[160:161]
	v_add_f32_e32 v108, v108, v109
	global_store_dwordx2 v[102:103], v[100:101], off
	v_mul_f32_e32 v100, v97, v97
	v_mul_f32_e32 v101, v99, v99
	v_add_f32_e32 v108, v174, v108
	v_add_f32_e32 v104, v104, v105
	v_fmac_f32_e32 v100, v96, v96
	v_fmac_f32_e32 v101, v98, v98
	v_add_f32_e32 v104, v108, v104
	v_add_f32_e32 v100, v100, v101
	v_add_f32_e32 v101, v104, v100
	ds_bpermute_b32 v102, v214, v101
	global_store_dwordx4 v[204:205], v[96:99], off offset:576
	v_or_b32_e32 v110, 0x120, v110
	v_readlane_b32 s61, v252, 17
	v_pk_mul_f32 v[96:97], v[112:113], v[96:97]
	v_pk_mul_f32 v[98:99], v[114:115], v[98:99]
	v_cvt_pk_bf16_f32 v100, v96, v97
	s_waitcnt lgkmcnt(0)
	v_add_f32_e32 v96, v101, v102
	ds_bpermute_b32 v97, v213, v96
	v_cvt_pk_bf16_f32 v101, v98, v99
	v_lshl_add_u64 v[98:99], s[14:15], 0, v[110:111]
	v_readlane_b32 s62, v252, 18
	v_readlane_b32 s63, v252, 19
	v_readlane_b32 s64, v252, 20
	v_readlane_b32 s65, v252, 21
	v_readlane_b32 s66, v252, 22
	v_readlane_b32 s67, v252, 23
	v_readlane_b32 s68, v252, 24
	v_readlane_b32 s69, v252, 25
	v_readlane_b32 s70, v252, 26
	v_readlane_b32 s71, v252, 27
	v_readlane_b32 s72, v252, 28
	v_readlane_b32 s73, v252, 29
	global_store_dwordx2 v[98:99], v[100:101], off
	s_and_saveexec_b64 s[28:29], s[2:3]
	s_cbranch_execz .LBB0_856
	v_lshl_add_u64 v[98:99], v[202:203], 2, s[16:17]
	s_waitcnt lgkmcnt(0)
	v_add_f32_e32 v96, v96, v97
	v_mov_b32_e32 v243, v96
.LBB0_856:
	s_or_b64 exec, exec, s[28:29]
	v_add_u32_e32 v160, 0x80, v200
	v_ashrrev_i32_e32 v161, 31, v160
	v_readlane_b32 s60, v252, 16
	s_waitcnt lgkmcnt(0)
	v_lshlrev_b64 v[96:97], 13, v[160:161]
	v_readlane_b32 s74, v252, 30
	v_readlane_b32 s75, v252, 31
	v_pk_add_f32 v[94:95], v[94:95], v[158:159]
	v_pk_add_f32 v[92:93], v[92:93], v[156:157]
	v_lshl_add_u64 v[96:97], s[74:75], 0, v[96:97]
	v_lshl_add_u64 v[162:163], v[188:189], 2, v[96:97]
	global_load_dwordx4 v[108:111], v[162:163], off
	global_load_dwordx4 v[104:107], v[162:163], off offset:64
	global_load_dwordx4 v[100:103], v[162:163], off offset:512
	global_load_dwordx4 v[96:99], v[162:163], off offset:576
	v_lshlrev_b64 v[164:165], 11, v[192:193]
	v_mul_f32_e32 v156, v93, v93
	v_mul_f32_e32 v157, v95, v95
	v_lshl_add_u64 v[164:165], v[164:165], 0, v[188:189]
	global_store_dwordx4 v[194:195], v[92:95], off
	v_fmac_f32_e32 v156, v92, v92
	v_fmac_f32_e32 v157, v94, v94
	v_pk_mul_f32 v[94:95], v[130:131], v[94:95]
	v_pk_mul_f32 v[92:93], v[128:129], v[92:93]
	v_add_f32_e32 v158, v156, v157
	v_cvt_pk_bf16_f32 v92, v92, v93
	v_cvt_pk_bf16_f32 v93, v94, v95
	v_lshlrev_b64 v[94:95], 1, v[164:165]
	v_lshl_add_u64 v[156:157], s[14:15], 0, v[94:95]
	v_pk_add_f32 v[90:91], v[90:91], v[154:155]
	v_pk_add_f32 v[88:89], v[88:89], v[152:153]
	global_store_dwordx2 v[156:157], v[92:93], off
	v_mul_f32_e32 v92, v89, v89
	v_mul_f32_e32 v93, v91, v91
	global_store_dwordx4 v[194:195], v[88:91], off offset:64
	v_fmac_f32_e32 v92, v88, v88
	v_fmac_f32_e32 v93, v90, v90
	v_pk_mul_f32 v[90:91], v[122:123], v[90:91]
	v_pk_mul_f32 v[88:89], v[120:121], v[88:89]
	v_pk_add_f32 v[86:87], v[86:87], v[150:151]
	v_cvt_pk_bf16_f32 v88, v88, v89
	v_cvt_pk_bf16_f32 v89, v90, v91
	v_or_b32_e32 v90, 32, v94
	v_mov_b32_e32 v91, v95
	v_lshl_add_u64 v[90:91], s[14:15], 0, v[90:91]
	v_pk_add_f32 v[84:85], v[84:85], v[148:149]
	global_store_dwordx2 v[90:91], v[88:89], off
	v_mul_f32_e32 v88, v85, v85
	v_mul_f32_e32 v89, v87, v87
	global_store_dwordx4 v[194:195], v[84:87], off offset:512
	v_fmac_f32_e32 v88, v84, v84
	v_fmac_f32_e32 v89, v86, v86
	v_pk_mul_f32 v[86:87], v[118:119], v[86:87]
	v_pk_mul_f32 v[84:85], v[116:117], v[84:85]
	v_pk_add_f32 v[82:83], v[82:83], v[146:147]
	v_cvt_pk_bf16_f32 v84, v84, v85
	v_cvt_pk_bf16_f32 v85, v86, v87
	v_or_b32_e32 v86, 0x100, v94
	v_mov_b32_e32 v87, v95
	v_lshl_add_u64 v[86:87], s[14:15], 0, v[86:87]
	v_pk_add_f32 v[80:81], v[80:81], v[144:145]
	v_add_f32_e32 v92, v92, v93
	global_store_dwordx2 v[86:87], v[84:85], off
	v_mul_f32_e32 v84, v81, v81
	v_mul_f32_e32 v85, v83, v83
	v_add_f32_e32 v92, v158, v92
	v_add_f32_e32 v88, v88, v89
	v_fmac_f32_e32 v84, v80, v80
	v_fmac_f32_e32 v85, v82, v82
	v_add_f32_e32 v88, v92, v88
	v_add_f32_e32 v84, v84, v85
	v_add_f32_e32 v85, v88, v84
	ds_bpermute_b32 v86, v214, v85
	global_store_dwordx4 v[194:195], v[80:83], off offset:576
	v_or_b32_e32 v94, 0x120, v94
	v_readlane_b32 s61, v252, 17
	v_pk_mul_f32 v[80:81], v[112:113], v[80:81]
	v_pk_mul_f32 v[82:83], v[114:115], v[82:83]
	v_cvt_pk_bf16_f32 v84, v80, v81
	s_waitcnt lgkmcnt(0)
	v_add_f32_e32 v80, v85, v86
	ds_bpermute_b32 v81, v213, v80
	v_cvt_pk_bf16_f32 v85, v82, v83
	v_lshl_add_u64 v[82:83], s[14:15], 0, v[94:95]
	v_readlane_b32 s62, v252, 18
	v_readlane_b32 s63, v252, 19
	v_readlane_b32 s64, v252, 20
	v_readlane_b32 s65, v252, 21
	v_readlane_b32 s66, v252, 22
	v_readlane_b32 s67, v252, 23
	v_readlane_b32 s68, v252, 24
	v_readlane_b32 s69, v252, 25
	v_readlane_b32 s70, v252, 26
	v_readlane_b32 s71, v252, 27
	v_readlane_b32 s72, v252, 28
	v_readlane_b32 s73, v252, 29
	global_store_dwordx2 v[82:83], v[84:85], off
	s_and_saveexec_b64 s[28:29], s[2:3]
	s_cbranch_execz .LBB0_858
	v_lshl_add_u64 v[82:83], v[192:193], 2, s[16:17]
	s_waitcnt lgkmcnt(0)
	v_add_f32_e32 v80, v80, v81
	v_mov_b32_e32 v244, v80
.LBB0_858:
	s_or_b64 exec, exec, s[28:29]
	s_waitcnt lgkmcnt(0)
	v_lshl_add_u64 v[80:81], v[188:189], 2, v[190:191]
	v_lshl_add_u64 v[144:145], v[80:81], 0, s[24:25]
	v_add_co_u32_e32 v80, vcc, 0x120000, v80
	s_waitcnt vmcnt(21)
	v_pk_add_f32 v[78:79], v[78:79], v[142:143]
	v_addc_co_u32_e32 v81, vcc, 0, v81, vcc
	global_load_dwordx4 v[88:91], v[144:145], off offset:64
	global_load_dwordx4 v[84:87], v[144:145], off offset:512
	global_load_dwordx4 v[92:95], v[80:81], off
	s_nop 0
	global_load_dwordx4 v[80:83], v[144:145], off offset:576
	v_pk_add_f32 v[76:77], v[76:77], v[140:141]
	v_lshlrev_b64 v[146:147], 11, v[196:197]
	v_mul_f32_e32 v140, v77, v77
	v_mul_f32_e32 v141, v79, v79
	v_lshl_add_u64 v[146:147], v[146:147], 0, v[188:189]
	global_store_dwordx4 v[198:199], v[76:79], off
	v_fmac_f32_e32 v140, v76, v76
	v_fmac_f32_e32 v141, v78, v78
	v_pk_mul_f32 v[78:79], v[130:131], v[78:79]
	v_pk_mul_f32 v[76:77], v[128:129], v[76:77]
	v_add_f32_e32 v142, v140, v141
	v_cvt_pk_bf16_f32 v76, v76, v77
	v_cvt_pk_bf16_f32 v77, v78, v79
	v_lshlrev_b64 v[78:79], 1, v[146:147]
	v_lshl_add_u64 v[140:141], s[14:15], 0, v[78:79]
	s_waitcnt vmcnt(25)
	v_pk_add_f32 v[74:75], v[74:75], v[138:139]
	v_pk_add_f32 v[72:73], v[72:73], v[136:137]
	global_store_dwordx2 v[140:141], v[76:77], off
	v_mul_f32_e32 v76, v73, v73
	v_mul_f32_e32 v77, v75, v75
	global_store_dwordx4 v[198:199], v[72:75], off offset:64
	v_fmac_f32_e32 v76, v72, v72
	v_fmac_f32_e32 v77, v74, v74
	v_pk_mul_f32 v[74:75], v[122:123], v[74:75]
	v_pk_mul_f32 v[72:73], v[120:121], v[72:73]
	s_waitcnt vmcnt(26)
	v_pk_add_f32 v[70:71], v[70:71], v[134:135]
	v_cvt_pk_bf16_f32 v72, v72, v73
	v_cvt_pk_bf16_f32 v73, v74, v75
	v_or_b32_e32 v74, 32, v78
	v_mov_b32_e32 v75, v79
	v_lshl_add_u64 v[74:75], s[14:15], 0, v[74:75]
	v_pk_add_f32 v[68:69], v[68:69], v[132:133]
	global_store_dwordx2 v[74:75], v[72:73], off
	v_mul_f32_e32 v72, v69, v69
	v_mul_f32_e32 v73, v71, v71
	global_store_dwordx4 v[198:199], v[68:71], off offset:512
	v_fmac_f32_e32 v72, v68, v68
	v_fmac_f32_e32 v73, v70, v70
	v_pk_mul_f32 v[70:71], v[118:119], v[70:71]
	v_pk_mul_f32 v[68:69], v[116:117], v[68:69]
	s_waitcnt vmcnt(27)
	v_pk_add_f32 v[66:67], v[66:67], v[126:127]
	v_cvt_pk_bf16_f32 v68, v68, v69
	v_cvt_pk_bf16_f32 v69, v70, v71
	v_or_b32_e32 v70, 0x100, v78
	v_mov_b32_e32 v71, v79
	v_lshl_add_u64 v[70:71], s[14:15], 0, v[70:71]
	v_pk_add_f32 v[64:65], v[64:65], v[124:125]
	v_add_f32_e32 v76, v76, v77
	global_store_dwordx2 v[70:71], v[68:69], off
	v_mul_f32_e32 v68, v65, v65
	v_mul_f32_e32 v69, v67, v67
	v_add_f32_e32 v76, v142, v76
	v_add_f32_e32 v72, v72, v73
	v_fmac_f32_e32 v68, v64, v64
	v_fmac_f32_e32 v69, v66, v66
	v_add_f32_e32 v72, v76, v72
	v_add_f32_e32 v68, v68, v69
	v_add_f32_e32 v69, v72, v68
	ds_bpermute_b32 v70, v214, v69
	global_store_dwordx4 v[198:199], v[64:67], off offset:576
	v_or_b32_e32 v78, 0x120, v78
	s_nop 0
	v_pk_mul_f32 v[64:65], v[112:113], v[64:65]
	v_pk_mul_f32 v[66:67], v[114:115], v[66:67]
	v_cvt_pk_bf16_f32 v68, v64, v65
	s_waitcnt lgkmcnt(0)
	v_add_f32_e32 v64, v69, v70
	ds_bpermute_b32 v65, v213, v64
	v_cvt_pk_bf16_f32 v69, v66, v67
	v_lshl_add_u64 v[66:67], s[14:15], 0, v[78:79]
	global_store_dwordx2 v[66:67], v[68:69], off
	s_and_saveexec_b64 s[28:29], s[2:3]
	s_cbranch_execz .LBB0_860
	v_lshl_add_u64 v[66:67], v[196:197], 2, s[16:17]
	s_waitcnt lgkmcnt(0)
	v_add_f32_e32 v64, v64, v65
	v_mov_b32_e32 v245, v64
.LBB0_860:
	s_or_b64 exec, exec, s[28:29]
	v_or_b32_e32 v124, 32, v160
	v_ashrrev_i32_e32 v125, 31, v124
	v_readlane_b32 s60, v252, 16
	s_waitcnt lgkmcnt(0)
	v_lshlrev_b64 v[64:65], 13, v[124:125]
	v_readlane_b32 s74, v252, 30
	v_readlane_b32 s75, v252, 31
	s_waitcnt vmcnt(21)
	v_pk_add_f32 v[62:63], v[62:63], v[110:111]
	v_pk_add_f32 v[60:61], v[60:61], v[108:109]
	v_lshl_add_u64 v[64:65], s[74:75], 0, v[64:65]
	v_lshl_add_u64 v[126:127], v[188:189], 2, v[64:65]
	global_load_dwordx4 v[76:79], v[126:127], off
	global_load_dwordx4 v[72:75], v[126:127], off offset:64
	global_load_dwordx4 v[68:71], v[126:127], off offset:512
	global_load_dwordx4 v[64:67], v[126:127], off offset:576
	v_lshlrev_b64 v[132:133], 11, v[160:161]
	v_mul_f32_e32 v108, v61, v61
	v_mul_f32_e32 v109, v63, v63
	v_lshl_add_u64 v[132:133], v[132:133], 0, v[188:189]
	global_store_dwordx4 v[162:163], v[60:63], off
	v_fmac_f32_e32 v108, v60, v60
	v_fmac_f32_e32 v109, v62, v62
	v_pk_mul_f32 v[62:63], v[130:131], v[62:63]
	v_pk_mul_f32 v[60:61], v[128:129], v[60:61]
	v_add_f32_e32 v110, v108, v109
	v_cvt_pk_bf16_f32 v60, v60, v61
	v_cvt_pk_bf16_f32 v61, v62, v63
	v_lshlrev_b64 v[62:63], 1, v[132:133]
	v_lshl_add_u64 v[108:109], s[14:15], 0, v[62:63]
	s_waitcnt vmcnt(25)
	v_pk_add_f32 v[58:59], v[58:59], v[106:107]
	v_pk_add_f32 v[56:57], v[56:57], v[104:105]
	global_store_dwordx2 v[108:109], v[60:61], off
	v_mul_f32_e32 v60, v57, v57
	v_mul_f32_e32 v61, v59, v59
	global_store_dwordx4 v[162:163], v[56:59], off offset:64
	v_fmac_f32_e32 v60, v56, v56
	v_fmac_f32_e32 v61, v58, v58
	v_pk_mul_f32 v[58:59], v[122:123], v[58:59]
	v_pk_mul_f32 v[56:57], v[120:121], v[56:57]
	s_waitcnt vmcnt(26)
	v_pk_add_f32 v[54:55], v[54:55], v[102:103]
	v_cvt_pk_bf16_f32 v56, v56, v57
	v_cvt_pk_bf16_f32 v57, v58, v59
	v_or_b32_e32 v58, 32, v62
	v_mov_b32_e32 v59, v63
	v_lshl_add_u64 v[58:59], s[14:15], 0, v[58:59]
	v_pk_add_f32 v[52:53], v[52:53], v[100:101]
	global_store_dwordx2 v[58:59], v[56:57], off
	v_mul_f32_e32 v56, v53, v53
	v_mul_f32_e32 v57, v55, v55
	global_store_dwordx4 v[162:163], v[52:55], off offset:512
	v_fmac_f32_e32 v56, v52, v52
	v_fmac_f32_e32 v57, v54, v54
	v_pk_mul_f32 v[54:55], v[118:119], v[54:55]
	v_pk_mul_f32 v[52:53], v[116:117], v[52:53]
	s_waitcnt vmcnt(27)
	v_pk_add_f32 v[50:51], v[50:51], v[98:99]
	v_cvt_pk_bf16_f32 v52, v52, v53
	v_cvt_pk_bf16_f32 v53, v54, v55
	v_or_b32_e32 v54, 0x100, v62
	v_mov_b32_e32 v55, v63
	v_lshl_add_u64 v[54:55], s[14:15], 0, v[54:55]
	v_pk_add_f32 v[48:49], v[48:49], v[96:97]
	v_add_f32_e32 v60, v60, v61
	global_store_dwordx2 v[54:55], v[52:53], off
	v_mul_f32_e32 v52, v49, v49
	v_mul_f32_e32 v53, v51, v51
	v_add_f32_e32 v60, v110, v60
	v_add_f32_e32 v56, v56, v57
	v_fmac_f32_e32 v52, v48, v48
	v_fmac_f32_e32 v53, v50, v50
	v_add_f32_e32 v56, v60, v56
	v_add_f32_e32 v52, v52, v53
	v_add_f32_e32 v53, v56, v52
	ds_bpermute_b32 v54, v214, v53
	global_store_dwordx4 v[162:163], v[48:51], off offset:576
	v_or_b32_e32 v62, 0x120, v62
	v_readlane_b32 s61, v252, 17
	v_pk_mul_f32 v[48:49], v[112:113], v[48:49]
	v_pk_mul_f32 v[50:51], v[114:115], v[50:51]
	v_cvt_pk_bf16_f32 v52, v48, v49
	s_waitcnt lgkmcnt(0)
	v_add_f32_e32 v48, v53, v54
	ds_bpermute_b32 v49, v213, v48
	v_cvt_pk_bf16_f32 v53, v50, v51
	v_lshl_add_u64 v[50:51], s[14:15], 0, v[62:63]
	v_readlane_b32 s62, v252, 18
	v_readlane_b32 s63, v252, 19
	v_readlane_b32 s64, v252, 20
	v_readlane_b32 s65, v252, 21
	v_readlane_b32 s66, v252, 22
	v_readlane_b32 s67, v252, 23
	v_readlane_b32 s68, v252, 24
	v_readlane_b32 s69, v252, 25
	v_readlane_b32 s70, v252, 26
	v_readlane_b32 s71, v252, 27
	v_readlane_b32 s72, v252, 28
	v_readlane_b32 s73, v252, 29
	global_store_dwordx2 v[50:51], v[52:53], off
	s_and_saveexec_b64 s[28:29], s[2:3]
	s_cbranch_execz .LBB0_862
	v_lshl_add_u64 v[50:51], v[160:161], 2, s[16:17]
	s_waitcnt lgkmcnt(0)
	v_add_f32_e32 v48, v48, v49
	v_mov_b32_e32 v246, v48
.LBB0_862:
	s_or_b64 exec, exec, s[28:29]
	v_or_b32_e32 v96, 48, v160
	v_ashrrev_i32_e32 v97, 31, v96
	v_readlane_b32 s60, v252, 16
	s_waitcnt lgkmcnt(0)
	v_lshlrev_b64 v[48:49], 13, v[96:97]
	v_readlane_b32 s74, v252, 30
	v_readlane_b32 s75, v252, 31
	v_or_b32_e32 v100, 16, v160
	v_ashrrev_i32_e32 v101, 31, v100
	v_lshl_add_u64 v[48:49], s[74:75], 0, v[48:49]
	v_lshl_add_u64 v[98:99], v[188:189], 2, v[48:49]
	global_load_dwordx4 v[60:63], v[98:99], off
	global_load_dwordx4 v[56:59], v[98:99], off offset:64
	global_load_dwordx4 v[52:55], v[98:99], off offset:512
	global_load_dwordx4 v[48:51], v[98:99], off offset:576
	s_waitcnt vmcnt(23)
	v_pk_add_f32 v[46:47], v[46:47], v[94:95]
	v_pk_add_f32 v[44:45], v[44:45], v[92:93]
	v_lshlrev_b64 v[102:103], 11, v[100:101]
	v_mul_f32_e32 v92, v45, v45
	v_mul_f32_e32 v93, v47, v47
	v_lshl_add_u64 v[102:103], v[102:103], 0, v[188:189]
	global_store_dwordx4 v[144:145], v[44:47], off
	v_fmac_f32_e32 v92, v44, v44
	v_fmac_f32_e32 v93, v46, v46
	v_pk_mul_f32 v[46:47], v[130:131], v[46:47]
	v_pk_mul_f32 v[44:45], v[128:129], v[44:45]
	v_add_f32_e32 v94, v92, v93
	v_cvt_pk_bf16_f32 v44, v44, v45
	v_cvt_pk_bf16_f32 v45, v46, v47
	v_lshlrev_b64 v[46:47], 1, v[102:103]
	v_lshl_add_u64 v[92:93], s[14:15], 0, v[46:47]
	v_pk_add_f32 v[42:43], v[42:43], v[90:91]
	v_pk_add_f32 v[40:41], v[40:41], v[88:89]
	global_store_dwordx2 v[92:93], v[44:45], off
	v_mul_f32_e32 v44, v41, v41
	v_mul_f32_e32 v45, v43, v43
	global_store_dwordx4 v[144:145], v[40:43], off offset:64
	v_fmac_f32_e32 v44, v40, v40
	v_fmac_f32_e32 v45, v42, v42
	v_pk_mul_f32 v[42:43], v[122:123], v[42:43]
	v_pk_mul_f32 v[40:41], v[120:121], v[40:41]
	v_pk_add_f32 v[38:39], v[38:39], v[86:87]
	v_cvt_pk_bf16_f32 v40, v40, v41
	v_cvt_pk_bf16_f32 v41, v42, v43
	v_or_b32_e32 v42, 32, v46
	v_mov_b32_e32 v43, v47
	v_lshl_add_u64 v[42:43], s[14:15], 0, v[42:43]
	v_pk_add_f32 v[36:37], v[36:37], v[84:85]
	global_store_dwordx2 v[42:43], v[40:41], off
	v_mul_f32_e32 v40, v37, v37
	v_mul_f32_e32 v41, v39, v39
	global_store_dwordx4 v[144:145], v[36:39], off offset:512
	v_fmac_f32_e32 v40, v36, v36
	v_fmac_f32_e32 v41, v38, v38
	v_pk_mul_f32 v[38:39], v[118:119], v[38:39]
	v_pk_mul_f32 v[36:37], v[116:117], v[36:37]
	s_waitcnt vmcnt(27)
	v_pk_add_f32 v[34:35], v[34:35], v[82:83]
	v_cvt_pk_bf16_f32 v36, v36, v37
	v_cvt_pk_bf16_f32 v37, v38, v39
	v_or_b32_e32 v38, 0x100, v46
	v_mov_b32_e32 v39, v47
	v_lshl_add_u64 v[38:39], s[14:15], 0, v[38:39]
	v_pk_add_f32 v[32:33], v[32:33], v[80:81]
	v_add_f32_e32 v44, v44, v45
	global_store_dwordx2 v[38:39], v[36:37], off
	v_mul_f32_e32 v36, v33, v33
	v_mul_f32_e32 v37, v35, v35
	v_add_f32_e32 v44, v94, v44
	v_add_f32_e32 v40, v40, v41
	v_fmac_f32_e32 v36, v32, v32
	v_fmac_f32_e32 v37, v34, v34
	v_add_f32_e32 v40, v44, v40
	v_add_f32_e32 v36, v36, v37
	v_add_f32_e32 v37, v40, v36
	ds_bpermute_b32 v38, v214, v37
	global_store_dwordx4 v[144:145], v[32:35], off offset:576
	v_or_b32_e32 v46, 0x120, v46
	v_readlane_b32 s61, v252, 17
	v_pk_mul_f32 v[32:33], v[112:113], v[32:33]
	v_pk_mul_f32 v[34:35], v[114:115], v[34:35]
	v_cvt_pk_bf16_f32 v36, v32, v33
	s_waitcnt lgkmcnt(0)
	v_add_f32_e32 v32, v37, v38
	ds_bpermute_b32 v33, v213, v32
	v_cvt_pk_bf16_f32 v37, v34, v35
	v_lshl_add_u64 v[34:35], s[14:15], 0, v[46:47]
	v_readlane_b32 s62, v252, 18
	v_readlane_b32 s63, v252, 19
	v_readlane_b32 s64, v252, 20
	v_readlane_b32 s65, v252, 21
	v_readlane_b32 s66, v252, 22
	v_readlane_b32 s67, v252, 23
	v_readlane_b32 s68, v252, 24
	v_readlane_b32 s69, v252, 25
	v_readlane_b32 s70, v252, 26
	v_readlane_b32 s71, v252, 27
	v_readlane_b32 s72, v252, 28
	v_readlane_b32 s73, v252, 29
	global_store_dwordx2 v[34:35], v[36:37], off
	s_and_saveexec_b64 s[28:29], s[2:3]
	s_cbranch_execz .LBB0_864
	v_lshl_add_u64 v[34:35], v[100:101], 2, s[16:17]
	s_waitcnt lgkmcnt(0)
	v_add_f32_e32 v32, v32, v33
	v_mov_b32_e32 v247, v32
.LBB0_864:
	s_or_b64 exec, exec, s[28:29]
	s_waitcnt vmcnt(21)
	v_pk_add_f32 v[30:31], v[30:31], v[78:79]
	v_pk_add_f32 v[28:29], v[28:29], v[76:77]
	s_waitcnt lgkmcnt(0)
	v_lshlrev_b64 v[32:33], 11, v[124:125]
	v_mul_f32_e32 v34, v29, v29
	v_mul_f32_e32 v35, v31, v31
	v_lshl_add_u64 v[32:33], v[32:33], 0, v[188:189]
	global_store_dwordx4 v[126:127], v[28:31], off
	v_fmac_f32_e32 v34, v28, v28
	v_fmac_f32_e32 v35, v30, v30
	v_pk_mul_f32 v[30:31], v[130:131], v[30:31]
	v_pk_mul_f32 v[28:29], v[128:129], v[28:29]
	s_waitcnt vmcnt(21)
	v_pk_add_f32 v[26:27], v[26:27], v[74:75]
	v_cvt_pk_bf16_f32 v28, v28, v29
	v_cvt_pk_bf16_f32 v29, v30, v31
	v_lshlrev_b64 v[30:31], 1, v[32:33]
	v_lshl_add_u64 v[32:33], s[14:15], 0, v[30:31]
	v_pk_add_f32 v[24:25], v[24:25], v[72:73]
	global_store_dwordx2 v[32:33], v[28:29], off
	v_mul_f32_e32 v28, v25, v25
	v_mul_f32_e32 v29, v27, v27
	global_store_dwordx4 v[126:127], v[24:27], off offset:64
	v_fmac_f32_e32 v28, v24, v24
	v_fmac_f32_e32 v29, v26, v26
	v_pk_mul_f32 v[26:27], v[122:123], v[26:27]
	v_pk_mul_f32 v[24:25], v[120:121], v[24:25]
	s_waitcnt vmcnt(22)
	v_pk_add_f32 v[22:23], v[22:23], v[70:71]
	v_cvt_pk_bf16_f32 v24, v24, v25
	v_cvt_pk_bf16_f32 v25, v26, v27
	v_or_b32_e32 v26, 32, v30
	v_mov_b32_e32 v27, v31
	v_lshl_add_u64 v[26:27], s[14:15], 0, v[26:27]
	v_pk_add_f32 v[20:21], v[20:21], v[68:69]
	global_store_dwordx2 v[26:27], v[24:25], off
	v_mul_f32_e32 v24, v21, v21
	v_mul_f32_e32 v25, v23, v23
	global_store_dwordx4 v[126:127], v[20:23], off offset:512
	v_fmac_f32_e32 v24, v20, v20
	v_fmac_f32_e32 v25, v22, v22
	v_pk_mul_f32 v[22:23], v[118:119], v[22:23]
	v_pk_mul_f32 v[20:21], v[116:117], v[20:21]
	s_waitcnt vmcnt(23)
	v_pk_add_f32 v[18:19], v[18:19], v[66:67]
	v_cvt_pk_bf16_f32 v20, v20, v21
	v_cvt_pk_bf16_f32 v21, v22, v23
	v_or_b32_e32 v22, 0x100, v30
	v_mov_b32_e32 v23, v31
	v_lshl_add_u64 v[22:23], s[14:15], 0, v[22:23]
	v_pk_add_f32 v[16:17], v[16:17], v[64:65]
	v_add_f32_e32 v34, v34, v35
	v_add_f32_e32 v28, v28, v29
	global_store_dwordx2 v[22:23], v[20:21], off
	v_mul_f32_e32 v20, v17, v17
	v_mul_f32_e32 v21, v19, v19
	v_add_f32_e32 v28, v34, v28
	v_add_f32_e32 v24, v24, v25
	v_fmac_f32_e32 v20, v16, v16
	v_fmac_f32_e32 v21, v18, v18
	v_add_f32_e32 v24, v28, v24
	v_add_f32_e32 v20, v20, v21
	v_add_f32_e32 v21, v24, v20
	ds_bpermute_b32 v22, v214, v21
	global_store_dwordx4 v[126:127], v[16:19], off offset:576
	v_or_b32_e32 v30, 0x120, v30
	s_nop 0
	v_pk_mul_f32 v[16:17], v[112:113], v[16:17]
	v_pk_mul_f32 v[18:19], v[114:115], v[18:19]
	v_cvt_pk_bf16_f32 v20, v16, v17
	s_waitcnt lgkmcnt(0)
	v_add_f32_e32 v16, v21, v22
	ds_bpermute_b32 v17, v213, v16
	v_cvt_pk_bf16_f32 v21, v18, v19
	v_lshl_add_u64 v[18:19], s[14:15], 0, v[30:31]
	global_store_dwordx2 v[18:19], v[20:21], off
	s_and_saveexec_b64 s[28:29], s[2:3]
	s_cbranch_execz .LBB0_866
	v_lshl_add_u64 v[18:19], v[124:125], 2, s[16:17]
	s_waitcnt lgkmcnt(0)
	v_add_f32_e32 v16, v16, v17
	v_mov_b32_e32 v248, v16
.LBB0_866:
	s_or_b64 exec, exec, s[28:29]
	s_waitcnt vmcnt(17)
	v_pk_add_f32 v[14:15], v[14:15], v[62:63]
	v_pk_add_f32 v[12:13], v[12:13], v[60:61]
	s_waitcnt lgkmcnt(0)
	v_lshlrev_b64 v[16:17], 11, v[96:97]
	v_mul_f32_e32 v18, v13, v13
	v_mul_f32_e32 v19, v15, v15
	v_lshl_add_u64 v[16:17], v[16:17], 0, v[188:189]
	global_store_dwordx4 v[98:99], v[12:15], off
	v_fmac_f32_e32 v18, v12, v12
	v_fmac_f32_e32 v19, v14, v14
	v_pk_mul_f32 v[14:15], v[130:131], v[14:15]
	v_pk_mul_f32 v[12:13], v[128:129], v[12:13]
	s_waitcnt vmcnt(17)
	v_pk_add_f32 v[10:11], v[10:11], v[58:59]
	v_cvt_pk_bf16_f32 v12, v12, v13
	v_cvt_pk_bf16_f32 v13, v14, v15
	v_lshlrev_b64 v[14:15], 1, v[16:17]
	v_lshl_add_u64 v[16:17], s[14:15], 0, v[14:15]
	v_pk_add_f32 v[8:9], v[8:9], v[56:57]
	global_store_dwordx2 v[16:17], v[12:13], off
	v_mul_f32_e32 v12, v9, v9
	v_mul_f32_e32 v13, v11, v11
	global_store_dwordx4 v[98:99], v[8:11], off offset:64
	v_fmac_f32_e32 v12, v8, v8
	v_fmac_f32_e32 v13, v10, v10
	v_pk_mul_f32 v[10:11], v[122:123], v[10:11]
	v_pk_mul_f32 v[8:9], v[120:121], v[8:9]
	s_waitcnt vmcnt(18)
	v_pk_add_f32 v[6:7], v[6:7], v[54:55]
	v_cvt_pk_bf16_f32 v8, v8, v9
	v_cvt_pk_bf16_f32 v9, v10, v11
	v_or_b32_e32 v10, 32, v14
	v_mov_b32_e32 v11, v15
	v_lshl_add_u64 v[10:11], s[14:15], 0, v[10:11]
	v_pk_add_f32 v[4:5], v[4:5], v[52:53]
	global_store_dwordx2 v[10:11], v[8:9], off
	v_mul_f32_e32 v8, v5, v5
	v_mul_f32_e32 v9, v7, v7
	global_store_dwordx4 v[98:99], v[4:7], off offset:512
	v_fmac_f32_e32 v8, v4, v4
	v_fmac_f32_e32 v9, v6, v6
	v_pk_mul_f32 v[6:7], v[118:119], v[6:7]
	v_pk_mul_f32 v[4:5], v[116:117], v[4:5]
	s_waitcnt vmcnt(19)
	v_pk_add_f32 v[2:3], v[2:3], v[50:51]
	v_cvt_pk_bf16_f32 v4, v4, v5
	v_cvt_pk_bf16_f32 v5, v6, v7
	v_or_b32_e32 v6, 0x100, v14
	v_mov_b32_e32 v7, v15
	v_lshl_add_u64 v[6:7], s[14:15], 0, v[6:7]
	v_pk_add_f32 v[0:1], v[0:1], v[48:49]
	v_add_f32_e32 v18, v18, v19
	v_add_f32_e32 v12, v12, v13
	global_store_dwordx2 v[6:7], v[4:5], off
	v_mul_f32_e32 v4, v1, v1
	v_mul_f32_e32 v5, v3, v3
	v_add_f32_e32 v12, v18, v12
	v_add_f32_e32 v8, v8, v9
	v_fmac_f32_e32 v4, v0, v0
	v_fmac_f32_e32 v5, v2, v2
	v_add_f32_e32 v8, v12, v8
	v_add_f32_e32 v4, v4, v5
	v_add_f32_e32 v5, v8, v4
	ds_bpermute_b32 v6, v214, v5
	global_store_dwordx4 v[98:99], v[0:3], off offset:576
	v_or_b32_e32 v14, 0x120, v14
	s_nop 0
	v_pk_mul_f32 v[0:1], v[112:113], v[0:1]
	v_pk_mul_f32 v[2:3], v[114:115], v[2:3]
	v_cvt_pk_bf16_f32 v4, v0, v1
	s_waitcnt lgkmcnt(0)
	v_add_f32_e32 v0, v5, v6
	ds_bpermute_b32 v1, v213, v0
	v_cvt_pk_bf16_f32 v5, v2, v3
	v_lshl_add_u64 v[2:3], s[14:15], 0, v[14:15]
	global_store_dwordx2 v[2:3], v[4:5], off
	s_and_saveexec_b64 s[28:29], s[2:3]
	s_cbranch_execz .LBB0_868
	v_lshl_add_u64 v[2:3], v[96:97], 2, s[16:17]
	s_waitcnt lgkmcnt(0)
	v_add_f32_e32 v0, v0, v1
	global_atomic_add_f32 v[2:3], v0, off
	global_atomic_add_f32 v[2:3], v242, off offset:-704
	global_atomic_add_f32 v[2:3], v243, off offset:-640
	global_atomic_add_f32 v[2:3], v244, off offset:-576
	global_atomic_add_f32 v[2:3], v245, off offset:-512
	global_atomic_add_f32 v[2:3], v246, off offset:-192
	global_atomic_add_f32 v[2:3], v247, off offset:-128
	global_atomic_add_f32 v[2:3], v248, off offset:-64

.LBB0_1060:
	v_readlane_b32 s60, v252, 16
	v_lshl_add_u32 v64, s54, 8, v218
	v_readlane_b32 s61, v252, 17
	v_readlane_b32 s62, v252, 18
	v_readlane_b32 s63, v252, 19
	v_readlane_b32 s72, v252, 28
	v_readlane_b32 s73, v252, 29
	v_lshl_or_b32 v144, s55, 8, v221
	v_ashrrev_i32_e32 v65, 31, v64
	v_readlane_b32 s74, v252, 30
	v_readlane_b32 s75, v252, 31
	s_mov_b64 s[60:61], s[72:73]
	v_ashrrev_i32_e32 v145, 31, v144
	s_waitcnt lgkmcnt(0)
	v_lshlrev_b64 v[0:1], 13, v[64:65]
	s_mov_b64 s[62:63], s[74:75]
	v_lshlrev_b64 v[16:17], 2, v[144:145]
	v_lshl_add_u64 v[210:211], s[62:63], 0, v[0:1]
	v_readlane_b32 s66, v252, 22
	v_readlane_b32 s67, v252, 23
	v_lshl_add_u64 v[228:229], v[210:211], 0, v[16:17]
	s_mov_b64 s[54:55], s[66:67]
	global_load_dwordx4 v[28:31], v[228:229], off
	global_load_dwordx4 v[40:43], v[228:229], off offset:64
	global_load_dwordx4 v[52:55], v[228:229], off offset:512
	v_lshl_add_u64 v[0:1], s[54:55], 0, v[16:17]
	global_load_dwordx4 v[12:15], v[0:1], off
	global_load_dwordx4 v[8:11], v[0:1], off offset:64
	global_load_dwordx4 v[4:7], v[0:1], off offset:512
	global_load_dwordx4 v[60:63], v[228:229], off offset:576
	v_or_b32_e32 v66, 16, v64
	v_or_b32_e32 v212, 32, v64
	v_ashrrev_i32_e32 v67, 31, v66
	v_ashrrev_i32_e32 v213, 31, v212
	v_lshlrev_b64 v[18:19], 13, v[66:67]
	v_lshlrev_b64 v[20:21], 13, v[212:213]
	v_lshl_add_u64 v[18:19], s[62:63], 0, v[18:19]
	global_load_dwordx4 v[0:3], v[0:1], off offset:576
	v_lshl_add_u64 v[20:21], s[62:63], 0, v[20:21]
	v_lshl_add_u64 v[216:217], v[18:19], 0, v[16:17]
	v_lshl_add_u64 v[214:215], v[20:21], 0, v[16:17]
	global_load_dwordx4 v[56:59], v[216:217], off
	global_load_dwordx4 v[48:51], v[216:217], off offset:64
	global_load_dwordx4 v[36:39], v[216:217], off offset:512
	global_load_dwordx4 v[24:27], v[216:217], off offset:576
	global_load_dwordx4 v[44:47], v[214:215], off
	global_load_dwordx4 v[32:35], v[214:215], off offset:64
	global_load_dwordx4 v[20:23], v[214:215], off offset:512
	global_load_dwordx4 v[16:19], v[214:215], off offset:576
	v_and_b32_e32 v227, 64, v225
	v_xor_b32_e32 v226, 16, v225
	v_add_u32_e32 v227, 64, v227
	v_xor_b32_e32 v230, 32, v225
	v_cmp_lt_i32_e32 vcc, v226, v227
	v_readlane_b32 s64, v252, 20
	v_readlane_b32 s65, v252, 21
	v_cndmask_b32_e32 v226, v225, v226, vcc
	v_cmp_lt_i32_e32 vcc, v230, v227
	v_lshlrev_b32_e32 v227, 2, v226
	v_readlane_b32 s68, v252, 24
	v_cndmask_b32_e32 v232, v225, v230, vcc
	v_lshlrev_b64 v[230:231], 11, v[64:65]
	v_lshl_add_u64 v[230:231], v[230:231], 0, v[144:145]
	v_lshlrev_b64 v[230:231], 1, v[230:231]
	v_lshlrev_b32_e32 v226, 2, v232
	v_lshl_add_u64 v[232:233], s[12:13], 0, v[230:231]
	v_or_b32_e32 v234, 32, v230
	v_mov_b32_e32 v235, v231
	v_lshl_add_u64 v[234:235], s[12:13], 0, v[234:235]
	v_readlane_b32 s69, v252, 25
	v_readlane_b32 s70, v252, 26
	v_readlane_b32 s71, v252, 27
	s_waitcnt vmcnt(0)
	v_pk_add_f32 v[30:31], v[198:199], v[30:31]
	v_pk_add_f32 v[28:29], v[200:201], v[28:29]
	v_pk_add_f32 v[42:43], v[202:203], v[42:43]
	v_pk_add_f32 v[40:41], v[204:205], v[40:41]
	v_pk_add_f32 v[54:55], v[208:209], v[54:55]
	v_pk_add_f32 v[52:53], v[206:207], v[52:53]
	v_mul_f32_e32 v236, v29, v29
	v_mul_f32_e32 v237, v31, v31
	v_pk_mul_f32 v[198:199], v[14:15], v[30:31]
	v_pk_mul_f32 v[200:201], v[12:13], v[28:29]
	v_mul_f32_e32 v238, v41, v41
	v_mul_f32_e32 v239, v43, v43
	global_store_dwordx4 v[228:229], v[28:31], off
	v_mul_f32_e32 v240, v53, v53
	v_mul_f32_e32 v241, v55, v55
	v_fmac_f32_e32 v236, v28, v28
	v_fmac_f32_e32 v237, v30, v30
	v_cvt_pk_bf16_f32 v28, v200, v201
	v_cvt_pk_bf16_f32 v29, v198, v199
	v_fmac_f32_e32 v238, v40, v40
	v_fmac_f32_e32 v239, v42, v42
	v_fmac_f32_e32 v240, v52, v52
	v_fmac_f32_e32 v241, v54, v54
	v_add_f32_e32 v199, v236, v237
	global_store_dwordx2 v[232:233], v[28:29], off
	global_store_dwordx4 v[228:229], v[40:43], off offset:64
	v_add_f32_e32 v28, v238, v239
	v_add_f32_e32 v29, v240, v241
	v_add_f32_e32 v28, v199, v28
	v_pk_mul_f32 v[202:203], v[10:11], v[42:43]
	v_pk_mul_f32 v[204:205], v[8:9], v[40:41]
	v_pk_mul_f32 v[206:207], v[6:7], v[54:55]
	v_pk_mul_f32 v[208:209], v[4:5], v[52:53]
	v_add_f32_e32 v40, v28, v29
	v_or_b32_e32 v28, 0x100, v230
	v_mov_b32_e32 v29, v231
	v_cvt_pk_bf16_f32 v30, v204, v205
	v_cvt_pk_bf16_f32 v31, v202, v203
	v_cvt_pk_bf16_f32 v198, v208, v209
	v_cvt_pk_bf16_f32 v199, v206, v207
	v_lshl_add_u64 v[28:29], s[12:13], 0, v[28:29]
	global_store_dwordx2 v[234:235], v[30:31], off
	global_store_dwordx4 v[228:229], v[52:55], off offset:512
	global_store_dwordx2 v[28:29], v[198:199], off
	v_pk_add_f32 v[30:31], v[196:197], v[62:63]
	v_pk_add_f32 v[28:29], v[194:195], v[60:61]
	v_mul_f32_e32 v42, v31, v31
	v_mul_f32_e32 v41, v29, v29
	v_fmac_f32_e32 v41, v28, v28
	v_fmac_f32_e32 v42, v30, v30
	v_add_f32_e32 v41, v41, v42
	v_add_f32_e32 v41, v40, v41
	ds_bpermute_b32 v42, v227, v41
	global_store_dwordx4 v[228:229], v[28:31], off offset:576
	v_or_b32_e32 v230, 0x120, v230
	s_nop 0
	v_pk_mul_f32 v[28:29], v[0:1], v[28:29]
	v_pk_mul_f32 v[30:31], v[2:3], v[30:31]
	v_cvt_pk_bf16_f32 v40, v28, v29
	s_waitcnt lgkmcnt(0)
	v_add_f32_e32 v28, v41, v42
	ds_bpermute_b32 v29, v226, v28
	v_cvt_pk_bf16_f32 v41, v30, v31
	v_lshl_add_u64 v[30:31], s[12:13], 0, v[230:231]
	global_store_dwordx2 v[30:31], v[40:41], off
	s_and_saveexec_b64 s[24:25], s[2:3]
	s_cbranch_execz .LBB0_1062
	v_lshl_add_u64 v[30:31], v[64:65], 2, s[14:15]
	s_waitcnt lgkmcnt(0)
	v_add_f32_e32 v28, v28, v29
	v_mov_b32_e32 v242, v28
.LBB0_1062:
	s_or_b64 exec, exec, s[24:25]
	v_or_b32_e32 v194, 48, v64
	v_ashrrev_i32_e32 v195, 31, v194
	v_readlane_b32 s60, v252, 16
	s_waitcnt lgkmcnt(0)
	v_lshlrev_b64 v[28:29], 13, v[194:195]
	v_readlane_b32 s74, v252, 30
	v_readlane_b32 s75, v252, 31
	v_pk_add_f32 v[58:59], v[192:193], v[58:59]
	v_pk_add_f32 v[56:57], v[190:191], v[56:57]
	v_lshl_add_u64 v[28:29], s[74:75], 0, v[28:29]
	v_lshl_add_u64 v[196:197], v[144:145], 2, v[28:29]
	global_load_dwordx4 v[60:63], v[196:197], off
	global_load_dwordx4 v[52:55], v[196:197], off offset:64
	global_load_dwordx4 v[40:43], v[196:197], off offset:512
	global_load_dwordx4 v[28:31], v[196:197], off offset:576
	v_lshlrev_b64 v[198:199], 11, v[66:67]
	v_mul_f32_e32 v65, v57, v57
	v_mul_f32_e32 v190, v59, v59
	v_lshl_add_u64 v[198:199], v[198:199], 0, v[144:145]
	global_store_dwordx4 v[216:217], v[56:59], off
	v_fmac_f32_e32 v65, v56, v56
	v_fmac_f32_e32 v190, v58, v58
	v_pk_mul_f32 v[58:59], v[14:15], v[58:59]
	v_pk_mul_f32 v[56:57], v[12:13], v[56:57]
	v_add_f32_e32 v65, v65, v190
	v_cvt_pk_bf16_f32 v56, v56, v57
	v_cvt_pk_bf16_f32 v57, v58, v59
	v_lshlrev_b64 v[58:59], 1, v[198:199]
	v_lshl_add_u64 v[190:191], s[12:13], 0, v[58:59]
	v_pk_add_f32 v[50:51], v[188:189], v[50:51]
	v_pk_add_f32 v[48:49], v[186:187], v[48:49]
	global_store_dwordx2 v[190:191], v[56:57], off
	v_mul_f32_e32 v56, v49, v49
	v_mul_f32_e32 v57, v51, v51
	global_store_dwordx4 v[216:217], v[48:51], off offset:64
	v_fmac_f32_e32 v56, v48, v48
	v_fmac_f32_e32 v57, v50, v50
	v_pk_mul_f32 v[50:51], v[10:11], v[50:51]
	v_pk_mul_f32 v[48:49], v[8:9], v[48:49]
	v_pk_add_f32 v[38:39], v[184:185], v[38:39]
	v_cvt_pk_bf16_f32 v48, v48, v49
	v_cvt_pk_bf16_f32 v49, v50, v51
	v_or_b32_e32 v50, 32, v58
	v_mov_b32_e32 v51, v59
	v_lshl_add_u64 v[50:51], s[12:13], 0, v[50:51]
	v_pk_add_f32 v[36:37], v[182:183], v[36:37]
	global_store_dwordx2 v[50:51], v[48:49], off
	v_mul_f32_e32 v48, v37, v37
	v_mul_f32_e32 v49, v39, v39
	global_store_dwordx4 v[216:217], v[36:39], off offset:512
	v_fmac_f32_e32 v48, v36, v36
	v_fmac_f32_e32 v49, v38, v38
	v_pk_mul_f32 v[38:39], v[6:7], v[38:39]
	v_pk_mul_f32 v[36:37], v[4:5], v[36:37]
	v_pk_add_f32 v[26:27], v[180:181], v[26:27]
	v_cvt_pk_bf16_f32 v36, v36, v37
	v_cvt_pk_bf16_f32 v37, v38, v39
	v_or_b32_e32 v38, 0x100, v58
	v_mov_b32_e32 v39, v59
	v_lshl_add_u64 v[38:39], s[12:13], 0, v[38:39]
	v_pk_add_f32 v[24:25], v[178:179], v[24:25]
	v_add_f32_e32 v56, v56, v57
	global_store_dwordx2 v[38:39], v[36:37], off
	v_mul_f32_e32 v36, v25, v25
	v_mul_f32_e32 v37, v27, v27
	v_add_f32_e32 v56, v65, v56
	v_add_f32_e32 v48, v48, v49
	v_fmac_f32_e32 v36, v24, v24
	v_fmac_f32_e32 v37, v26, v26
	v_add_f32_e32 v48, v56, v48
	v_add_f32_e32 v36, v36, v37
	v_add_f32_e32 v37, v48, v36
	ds_bpermute_b32 v38, v227, v37
	global_store_dwordx4 v[216:217], v[24:27], off offset:576
	v_or_b32_e32 v58, 0x120, v58
	v_readlane_b32 s61, v252, 17
	v_pk_mul_f32 v[24:25], v[0:1], v[24:25]
	v_pk_mul_f32 v[26:27], v[2:3], v[26:27]
	v_cvt_pk_bf16_f32 v36, v24, v25
	s_waitcnt lgkmcnt(0)
	v_add_f32_e32 v24, v37, v38
	ds_bpermute_b32 v25, v226, v24
	v_cvt_pk_bf16_f32 v37, v26, v27
	v_lshl_add_u64 v[26:27], s[12:13], 0, v[58:59]
	v_readlane_b32 s62, v252, 18
	v_readlane_b32 s63, v252, 19
	v_readlane_b32 s64, v252, 20
	v_readlane_b32 s65, v252, 21
	v_readlane_b32 s66, v252, 22
	v_readlane_b32 s67, v252, 23
	v_readlane_b32 s68, v252, 24
	v_readlane_b32 s69, v252, 25
	v_readlane_b32 s70, v252, 26
	v_readlane_b32 s71, v252, 27
	v_readlane_b32 s72, v252, 28
	v_readlane_b32 s73, v252, 29
	global_store_dwordx2 v[26:27], v[36:37], off
	s_and_saveexec_b64 s[24:25], s[2:3]
	s_cbranch_execz .LBB0_1064
	v_lshl_add_u64 v[26:27], v[66:67], 2, s[14:15]
	s_waitcnt lgkmcnt(0)
	v_add_f32_e32 v24, v24, v25
	v_mov_b32_e32 v243, v24
.LBB0_1064:
	s_or_b64 exec, exec, s[24:25]
	v_add_u32_e32 v178, 0x80, v64
	v_ashrrev_i32_e32 v179, 31, v178
	v_readlane_b32 s60, v252, 16
	s_waitcnt lgkmcnt(0)
	v_lshlrev_b64 v[24:25], 13, v[178:179]
	v_readlane_b32 s74, v252, 30
	v_readlane_b32 s75, v252, 31
	v_pk_add_f32 v[46:47], v[176:177], v[46:47]
	v_pk_add_f32 v[44:45], v[174:175], v[44:45]
	v_lshl_add_u64 v[24:25], s[74:75], 0, v[24:25]
	v_lshl_add_u64 v[180:181], v[144:145], 2, v[24:25]
	global_load_dwordx4 v[64:67], v[180:181], off
	global_load_dwordx4 v[48:51], v[180:181], off offset:64
	global_load_dwordx4 v[36:39], v[180:181], off offset:512
	global_load_dwordx4 v[24:27], v[180:181], off offset:576
	v_lshlrev_b64 v[56:57], 11, v[212:213]
	v_mul_f32_e32 v58, v45, v45
	v_mul_f32_e32 v59, v47, v47
	v_lshl_add_u64 v[56:57], v[56:57], 0, v[144:145]
	global_store_dwordx4 v[214:215], v[44:47], off
	v_fmac_f32_e32 v58, v44, v44
	v_fmac_f32_e32 v59, v46, v46
	v_pk_mul_f32 v[46:47], v[14:15], v[46:47]
	v_pk_mul_f32 v[44:45], v[12:13], v[44:45]
	v_pk_add_f32 v[34:35], v[172:173], v[34:35]
	v_cvt_pk_bf16_f32 v44, v44, v45
	v_cvt_pk_bf16_f32 v45, v46, v47
	v_lshlrev_b64 v[46:47], 1, v[56:57]
	v_lshl_add_u64 v[56:57], s[12:13], 0, v[46:47]
	v_pk_add_f32 v[32:33], v[170:171], v[32:33]
	global_store_dwordx2 v[56:57], v[44:45], off
	v_mul_f32_e32 v44, v33, v33
	v_mul_f32_e32 v45, v35, v35
	global_store_dwordx4 v[214:215], v[32:35], off offset:64
	v_fmac_f32_e32 v44, v32, v32
	v_fmac_f32_e32 v45, v34, v34
	v_pk_mul_f32 v[34:35], v[10:11], v[34:35]
	v_pk_mul_f32 v[32:33], v[8:9], v[32:33]
	v_pk_add_f32 v[22:23], v[168:169], v[22:23]
	v_cvt_pk_bf16_f32 v32, v32, v33
	v_cvt_pk_bf16_f32 v33, v34, v35
	v_or_b32_e32 v34, 32, v46
	v_mov_b32_e32 v35, v47
	v_lshl_add_u64 v[34:35], s[12:13], 0, v[34:35]
	v_pk_add_f32 v[20:21], v[166:167], v[20:21]
	global_store_dwordx2 v[34:35], v[32:33], off
	v_mul_f32_e32 v32, v21, v21
	v_mul_f32_e32 v33, v23, v23
	global_store_dwordx4 v[214:215], v[20:23], off offset:512
	v_fmac_f32_e32 v32, v20, v20
	v_fmac_f32_e32 v33, v22, v22
	v_pk_mul_f32 v[22:23], v[6:7], v[22:23]
	v_pk_mul_f32 v[20:21], v[4:5], v[20:21]
	v_pk_add_f32 v[18:19], v[164:165], v[18:19]
	v_cvt_pk_bf16_f32 v20, v20, v21
	v_cvt_pk_bf16_f32 v21, v22, v23
	v_or_b32_e32 v22, 0x100, v46
	v_mov_b32_e32 v23, v47
	v_lshl_add_u64 v[22:23], s[12:13], 0, v[22:23]
	v_pk_add_f32 v[16:17], v[162:163], v[16:17]
	v_add_f32_e32 v58, v58, v59
	v_add_f32_e32 v44, v44, v45
	global_store_dwordx2 v[22:23], v[20:21], off
	v_mul_f32_e32 v20, v17, v17
	v_mul_f32_e32 v21, v19, v19
	v_add_f32_e32 v44, v58, v44
	v_add_f32_e32 v32, v32, v33
	v_fmac_f32_e32 v20, v16, v16
	v_fmac_f32_e32 v21, v18, v18
	v_add_f32_e32 v32, v44, v32
	v_add_f32_e32 v20, v20, v21
	v_add_f32_e32 v21, v32, v20
	ds_bpermute_b32 v22, v227, v21
	global_store_dwordx4 v[214:215], v[16:19], off offset:576
	v_or_b32_e32 v46, 0x120, v46
	v_readlane_b32 s61, v252, 17
	v_pk_mul_f32 v[16:17], v[0:1], v[16:17]
	v_pk_mul_f32 v[18:19], v[2:3], v[18:19]
	v_cvt_pk_bf16_f32 v20, v16, v17
	s_waitcnt lgkmcnt(0)
	v_add_f32_e32 v16, v21, v22
	ds_bpermute_b32 v17, v226, v16
	v_cvt_pk_bf16_f32 v21, v18, v19
	v_lshl_add_u64 v[18:19], s[12:13], 0, v[46:47]
	v_readlane_b32 s62, v252, 18
	v_readlane_b32 s63, v252, 19
	v_readlane_b32 s64, v252, 20
	v_readlane_b32 s65, v252, 21
	v_readlane_b32 s66, v252, 22
	v_readlane_b32 s67, v252, 23
	v_readlane_b32 s68, v252, 24
	v_readlane_b32 s69, v252, 25
	v_readlane_b32 s70, v252, 26
	v_readlane_b32 s71, v252, 27
	v_readlane_b32 s72, v252, 28
	v_readlane_b32 s73, v252, 29
	global_store_dwordx2 v[18:19], v[20:21], off
	s_and_saveexec_b64 s[24:25], s[2:3]
	s_cbranch_execz .LBB0_1066
	v_lshl_add_u64 v[18:19], v[212:213], 2, s[14:15]
	s_waitcnt lgkmcnt(0)
	v_add_f32_e32 v16, v16, v17
	v_mov_b32_e32 v244, v16
.LBB0_1066:
	s_or_b64 exec, exec, s[24:25]
	s_waitcnt lgkmcnt(0)
	v_lshl_add_u64 v[16:17], v[144:145], 2, v[210:211]
	v_lshl_add_u64 v[162:163], v[16:17], 0, s[20:21]
	v_add_co_u32_e32 v16, vcc, 0x120000, v16
	v_lshlrev_b64 v[20:21], 11, v[194:195]
	s_nop 0
	v_addc_co_u32_e32 v17, vcc, 0, v17, vcc
	global_load_dwordx4 v[44:47], v[162:163], off offset:64
	global_load_dwordx4 v[32:35], v[162:163], off offset:512
	global_load_dwordx4 v[56:59], v[16:17], off
	s_nop 0
	global_load_dwordx4 v[16:19], v[162:163], off offset:576
	v_lshl_add_u64 v[164:165], v[20:21], 0, v[144:145]
	s_waitcnt vmcnt(25)
	v_pk_add_f32 v[22:23], v[160:161], v[62:63]
	v_pk_add_f32 v[20:21], v[158:159], v[60:61]
	v_mul_f32_e32 v61, v23, v23
	v_mul_f32_e32 v60, v21, v21
	v_fmac_f32_e32 v60, v20, v20
	v_fmac_f32_e32 v61, v22, v22
	global_store_dwordx4 v[196:197], v[20:23], off
	v_add_f32_e32 v62, v60, v61
	v_lshlrev_b64 v[60:61], 1, v[164:165]
	v_pk_mul_f32 v[22:23], v[14:15], v[22:23]
	v_pk_mul_f32 v[20:21], v[12:13], v[20:21]
	s_nop 0
	v_cvt_pk_bf16_f32 v20, v20, v21
	v_cvt_pk_bf16_f32 v21, v22, v23
	v_lshl_add_u64 v[22:23], s[12:13], 0, v[60:61]
	global_store_dwordx2 v[22:23], v[20:21], off
	s_waitcnt vmcnt(26)
	v_pk_add_f32 v[22:23], v[156:157], v[54:55]
	v_pk_add_f32 v[20:21], v[154:155], v[52:53]
	v_mul_f32_e32 v53, v23, v23
	v_mul_f32_e32 v52, v21, v21
	global_store_dwordx4 v[196:197], v[20:23], off offset:64
	v_fmac_f32_e32 v52, v20, v20
	v_fmac_f32_e32 v53, v22, v22
	v_pk_mul_f32 v[22:23], v[10:11], v[22:23]
	v_pk_mul_f32 v[20:21], v[8:9], v[20:21]
	v_add_f32_e32 v52, v52, v53
	v_cvt_pk_bf16_f32 v20, v20, v21
	v_cvt_pk_bf16_f32 v21, v22, v23
	v_or_b32_e32 v22, 32, v60
	v_mov_b32_e32 v23, v61
	v_lshl_add_u64 v[22:23], s[12:13], 0, v[22:23]
	global_store_dwordx2 v[22:23], v[20:21], off
	s_waitcnt vmcnt(27)
	v_pk_add_f32 v[22:23], v[152:153], v[42:43]
	v_pk_add_f32 v[20:21], v[150:151], v[40:41]
	v_mul_f32_e32 v41, v23, v23
	v_mul_f32_e32 v40, v21, v21
	global_store_dwordx4 v[196:197], v[20:23], off offset:512
	v_fmac_f32_e32 v40, v20, v20
	v_fmac_f32_e32 v41, v22, v22
	v_pk_mul_f32 v[22:23], v[6:7], v[22:23]
	v_pk_mul_f32 v[20:21], v[4:5], v[20:21]
	v_add_f32_e32 v52, v62, v52
	v_cvt_pk_bf16_f32 v20, v20, v21
	v_cvt_pk_bf16_f32 v21, v22, v23
	v_or_b32_e32 v22, 0x100, v60
	v_mov_b32_e32 v23, v61
	v_lshl_add_u64 v[22:23], s[12:13], 0, v[22:23]
	global_store_dwordx2 v[22:23], v[20:21], off
	s_waitcnt vmcnt(28)
	v_pk_add_f32 v[22:23], v[148:149], v[30:31]
	v_pk_add_f32 v[20:21], v[146:147], v[28:29]
	v_mul_f32_e32 v29, v23, v23
	v_mul_f32_e32 v28, v21, v21
	v_add_f32_e32 v40, v40, v41
	v_fmac_f32_e32 v28, v20, v20
	v_fmac_f32_e32 v29, v22, v22
	v_add_f32_e32 v40, v52, v40
	v_add_f32_e32 v28, v28, v29
	v_add_f32_e32 v29, v40, v28
	ds_bpermute_b32 v30, v227, v29
	global_store_dwordx4 v[196:197], v[20:23], off offset:576
	v_or_b32_e32 v60, 0x120, v60
	s_nop 0
	v_pk_mul_f32 v[20:21], v[0:1], v[20:21]
	v_pk_mul_f32 v[22:23], v[2:3], v[22:23]
	v_cvt_pk_bf16_f32 v28, v20, v21
	s_waitcnt lgkmcnt(0)
	v_add_f32_e32 v20, v29, v30
	ds_bpermute_b32 v21, v226, v20
	v_cvt_pk_bf16_f32 v29, v22, v23
	v_lshl_add_u64 v[22:23], s[12:13], 0, v[60:61]
	global_store_dwordx2 v[22:23], v[28:29], off
	s_and_saveexec_b64 s[24:25], s[2:3]
	s_cbranch_execz .LBB0_1068
	v_lshl_add_u64 v[22:23], v[194:195], 2, s[14:15]
	s_waitcnt lgkmcnt(0)
	v_add_f32_e32 v20, v20, v21
	v_mov_b32_e32 v245, v20
.LBB0_1068:
	s_or_b64 exec, exec, s[24:25]
	v_or_b32_e32 v146, 32, v178
	v_ashrrev_i32_e32 v147, 31, v146
	v_readlane_b32 s60, v252, 16
	s_waitcnt lgkmcnt(0)
	v_lshlrev_b64 v[20:21], 13, v[146:147]
	v_readlane_b32 s74, v252, 30
	v_readlane_b32 s75, v252, 31
	v_lshlrev_b64 v[60:61], 11, v[178:179]
	v_lshl_add_u64 v[150:151], v[60:61], 0, v[144:145]
	v_lshl_add_u64 v[20:21], s[74:75], 0, v[20:21]
	v_lshl_add_u64 v[148:149], v[144:145], 2, v[20:21]
	global_load_dwordx4 v[52:55], v[148:149], off
	global_load_dwordx4 v[40:43], v[148:149], off offset:64
	global_load_dwordx4 v[28:31], v[148:149], off offset:512
	global_load_dwordx4 v[20:23], v[148:149], off offset:576
	s_waitcnt vmcnt(25)
	v_pk_add_f32 v[62:63], v[142:143], v[66:67]
	v_pk_add_f32 v[60:61], v[140:141], v[64:65]
	v_mul_f32_e32 v65, v63, v63
	v_mul_f32_e32 v64, v61, v61
	global_store_dwordx4 v[180:181], v[60:63], off
	v_fmac_f32_e32 v64, v60, v60
	v_fmac_f32_e32 v65, v62, v62
	v_pk_mul_f32 v[62:63], v[14:15], v[62:63]
	v_pk_mul_f32 v[60:61], v[12:13], v[60:61]
	v_add_f32_e32 v66, v64, v65
	v_cvt_pk_bf16_f32 v60, v60, v61
	v_cvt_pk_bf16_f32 v61, v62, v63
	v_lshlrev_b64 v[62:63], 1, v[150:151]
	v_lshl_add_u64 v[64:65], s[12:13], 0, v[62:63]
	s_waitcnt vmcnt(25)
	v_pk_add_f32 v[50:51], v[126:127], v[50:51]
	v_pk_add_f32 v[48:49], v[124:125], v[48:49]
	global_store_dwordx2 v[64:65], v[60:61], off
	v_mul_f32_e32 v60, v49, v49
	v_mul_f32_e32 v61, v51, v51
	global_store_dwordx4 v[180:181], v[48:51], off offset:64
	v_fmac_f32_e32 v60, v48, v48
	v_fmac_f32_e32 v61, v50, v50
	v_pk_mul_f32 v[50:51], v[10:11], v[50:51]
	v_pk_mul_f32 v[48:49], v[8:9], v[48:49]
	s_waitcnt vmcnt(26)
	v_pk_add_f32 v[38:39], v[122:123], v[38:39]
	v_cvt_pk_bf16_f32 v48, v48, v49
	v_cvt_pk_bf16_f32 v49, v50, v51
	v_or_b32_e32 v50, 32, v62
	v_mov_b32_e32 v51, v63
	v_lshl_add_u64 v[50:51], s[12:13], 0, v[50:51]
	v_pk_add_f32 v[36:37], v[120:121], v[36:37]
	global_store_dwordx2 v[50:51], v[48:49], off
	v_mul_f32_e32 v48, v37, v37
	v_mul_f32_e32 v49, v39, v39
	global_store_dwordx4 v[180:181], v[36:39], off offset:512
	v_fmac_f32_e32 v48, v36, v36
	v_fmac_f32_e32 v49, v38, v38
	v_pk_mul_f32 v[38:39], v[6:7], v[38:39]
	v_pk_mul_f32 v[36:37], v[4:5], v[36:37]
	s_waitcnt vmcnt(27)
	v_pk_add_f32 v[26:27], v[118:119], v[26:27]
	v_cvt_pk_bf16_f32 v36, v36, v37
	v_cvt_pk_bf16_f32 v37, v38, v39
	v_or_b32_e32 v38, 0x100, v62
	v_mov_b32_e32 v39, v63
	v_lshl_add_u64 v[38:39], s[12:13], 0, v[38:39]
	v_pk_add_f32 v[24:25], v[116:117], v[24:25]
	v_add_f32_e32 v60, v60, v61
	global_store_dwordx2 v[38:39], v[36:37], off
	v_mul_f32_e32 v36, v25, v25
	v_mul_f32_e32 v37, v27, v27
	v_add_f32_e32 v60, v66, v60
	v_add_f32_e32 v48, v48, v49
	v_fmac_f32_e32 v36, v24, v24
	v_fmac_f32_e32 v37, v26, v26
	v_add_f32_e32 v48, v60, v48
	v_add_f32_e32 v36, v36, v37
	v_add_f32_e32 v37, v48, v36
	ds_bpermute_b32 v38, v227, v37
	global_store_dwordx4 v[180:181], v[24:27], off offset:576
	v_or_b32_e32 v62, 0x120, v62
	v_readlane_b32 s61, v252, 17
	v_pk_mul_f32 v[24:25], v[0:1], v[24:25]
	v_pk_mul_f32 v[26:27], v[2:3], v[26:27]
	v_cvt_pk_bf16_f32 v36, v24, v25
	s_waitcnt lgkmcnt(0)
	v_add_f32_e32 v24, v37, v38
	ds_bpermute_b32 v25, v226, v24
	v_cvt_pk_bf16_f32 v37, v26, v27
	v_lshl_add_u64 v[26:27], s[12:13], 0, v[62:63]
	v_readlane_b32 s62, v252, 18
	v_readlane_b32 s63, v252, 19
	v_readlane_b32 s64, v252, 20
	v_readlane_b32 s65, v252, 21
	v_readlane_b32 s66, v252, 22
	v_readlane_b32 s67, v252, 23
	v_readlane_b32 s68, v252, 24
	v_readlane_b32 s69, v252, 25
	v_readlane_b32 s70, v252, 26
	v_readlane_b32 s71, v252, 27
	v_readlane_b32 s72, v252, 28
	v_readlane_b32 s73, v252, 29
	global_store_dwordx2 v[26:27], v[36:37], off
	s_and_saveexec_b64 s[24:25], s[2:3]
	s_cbranch_execz .LBB0_1070
	v_lshl_add_u64 v[26:27], v[178:179], 2, s[14:15]
	s_waitcnt lgkmcnt(0)
	v_add_f32_e32 v24, v24, v25
	v_mov_b32_e32 v246, v24
.LBB0_1070:
	s_or_b64 exec, exec, s[24:25]
	v_or_b32_e32 v64, 48, v178
	v_ashrrev_i32_e32 v65, 31, v64
	v_readlane_b32 s60, v252, 16
	s_waitcnt lgkmcnt(0)
	v_lshlrev_b64 v[24:25], 13, v[64:65]
	v_readlane_b32 s74, v252, 30
	v_readlane_b32 s75, v252, 31
	v_or_b32_e32 v116, 16, v178
	v_ashrrev_i32_e32 v117, 31, v116
	v_lshl_add_u64 v[24:25], s[74:75], 0, v[24:25]
	v_lshl_add_u64 v[66:67], v[144:145], 2, v[24:25]
	global_load_dwordx4 v[60:63], v[66:67], off
	global_load_dwordx4 v[48:51], v[66:67], off offset:64
	global_load_dwordx4 v[36:39], v[66:67], off offset:512
	global_load_dwordx4 v[24:27], v[66:67], off offset:576
	s_waitcnt vmcnt(23)
	v_pk_add_f32 v[58:59], v[114:115], v[58:59]
	v_pk_add_f32 v[56:57], v[112:113], v[56:57]
	v_lshlrev_b64 v[118:119], 11, v[116:117]
	v_mul_f32_e32 v112, v57, v57
	v_mul_f32_e32 v113, v59, v59
	v_lshl_add_u64 v[118:119], v[118:119], 0, v[144:145]
	global_store_dwordx4 v[162:163], v[56:59], off
	v_fmac_f32_e32 v112, v56, v56
	v_fmac_f32_e32 v113, v58, v58
	v_pk_mul_f32 v[58:59], v[14:15], v[58:59]
	v_pk_mul_f32 v[56:57], v[12:13], v[56:57]
	v_add_f32_e32 v114, v112, v113
	v_cvt_pk_bf16_f32 v56, v56, v57
	v_cvt_pk_bf16_f32 v57, v58, v59
	v_lshlrev_b64 v[58:59], 1, v[118:119]
	v_lshl_add_u64 v[112:113], s[12:13], 0, v[58:59]
	v_pk_add_f32 v[46:47], v[110:111], v[46:47]
	v_pk_add_f32 v[44:45], v[108:109], v[44:45]
	global_store_dwordx2 v[112:113], v[56:57], off
	v_mul_f32_e32 v56, v45, v45
	v_mul_f32_e32 v57, v47, v47
	global_store_dwordx4 v[162:163], v[44:47], off offset:64
	v_fmac_f32_e32 v56, v44, v44
	v_fmac_f32_e32 v57, v46, v46
	v_pk_mul_f32 v[46:47], v[10:11], v[46:47]
	v_pk_mul_f32 v[44:45], v[8:9], v[44:45]
	v_pk_add_f32 v[34:35], v[106:107], v[34:35]
	v_cvt_pk_bf16_f32 v44, v44, v45
	v_cvt_pk_bf16_f32 v45, v46, v47
	v_or_b32_e32 v46, 32, v58
	v_mov_b32_e32 v47, v59
	v_lshl_add_u64 v[46:47], s[12:13], 0, v[46:47]
	v_pk_add_f32 v[32:33], v[104:105], v[32:33]
	global_store_dwordx2 v[46:47], v[44:45], off
	v_mul_f32_e32 v44, v33, v33
	v_mul_f32_e32 v45, v35, v35
	global_store_dwordx4 v[162:163], v[32:35], off offset:512
	v_fmac_f32_e32 v44, v32, v32
	v_fmac_f32_e32 v45, v34, v34
	v_pk_mul_f32 v[34:35], v[6:7], v[34:35]
	v_pk_mul_f32 v[32:33], v[4:5], v[32:33]
	s_waitcnt vmcnt(27)
	v_pk_add_f32 v[18:19], v[102:103], v[18:19]
	v_cvt_pk_bf16_f32 v32, v32, v33
	v_cvt_pk_bf16_f32 v33, v34, v35
	v_or_b32_e32 v34, 0x100, v58
	v_mov_b32_e32 v35, v59
	v_lshl_add_u64 v[34:35], s[12:13], 0, v[34:35]
	v_pk_add_f32 v[16:17], v[100:101], v[16:17]
	v_add_f32_e32 v56, v56, v57
	global_store_dwordx2 v[34:35], v[32:33], off
	v_mul_f32_e32 v32, v17, v17
	v_mul_f32_e32 v33, v19, v19
	v_add_f32_e32 v56, v114, v56
	v_add_f32_e32 v44, v44, v45
	v_fmac_f32_e32 v32, v16, v16
	v_fmac_f32_e32 v33, v18, v18
	v_add_f32_e32 v44, v56, v44
	v_add_f32_e32 v32, v32, v33
	v_add_f32_e32 v33, v44, v32
	ds_bpermute_b32 v34, v227, v33
	global_store_dwordx4 v[162:163], v[16:19], off offset:576
	v_or_b32_e32 v58, 0x120, v58
	v_readlane_b32 s61, v252, 17
	v_pk_mul_f32 v[16:17], v[0:1], v[16:17]
	v_pk_mul_f32 v[18:19], v[2:3], v[18:19]
	v_cvt_pk_bf16_f32 v32, v16, v17
	s_waitcnt lgkmcnt(0)
	v_add_f32_e32 v16, v33, v34
	ds_bpermute_b32 v17, v226, v16
	v_cvt_pk_bf16_f32 v33, v18, v19
	v_lshl_add_u64 v[18:19], s[12:13], 0, v[58:59]
	v_readlane_b32 s62, v252, 18
	v_readlane_b32 s63, v252, 19
	v_readlane_b32 s64, v252, 20
	v_readlane_b32 s65, v252, 21
	v_readlane_b32 s66, v252, 22
	v_readlane_b32 s67, v252, 23
	v_readlane_b32 s68, v252, 24
	v_readlane_b32 s69, v252, 25
	v_readlane_b32 s70, v252, 26
	v_readlane_b32 s71, v252, 27
	v_readlane_b32 s72, v252, 28
	v_readlane_b32 s73, v252, 29
	global_store_dwordx2 v[18:19], v[32:33], off
	s_and_saveexec_b64 s[24:25], s[2:3]
	s_cbranch_execz .LBB0_1072
	v_lshl_add_u64 v[18:19], v[116:117], 2, s[14:15]
	s_waitcnt lgkmcnt(0)
	v_add_f32_e32 v16, v16, v17
	v_mov_b32_e32 v247, v16
.LBB0_1072:
	s_or_b64 exec, exec, s[24:25]
	s_waitcnt lgkmcnt(0)
	v_lshlrev_b64 v[16:17], 11, v[146:147]
	v_lshl_add_u64 v[32:33], v[16:17], 0, v[144:145]
	s_waitcnt vmcnt(21)
	v_pk_add_f32 v[18:19], v[98:99], v[54:55]
	v_pk_add_f32 v[16:17], v[96:97], v[52:53]
	v_mul_f32_e32 v35, v19, v19
	v_mul_f32_e32 v34, v17, v17
	global_store_dwordx4 v[148:149], v[16:19], off
	v_fmac_f32_e32 v34, v16, v16
	v_fmac_f32_e32 v35, v18, v18
	v_pk_mul_f32 v[18:19], v[14:15], v[18:19]
	v_pk_mul_f32 v[16:17], v[12:13], v[16:17]
	v_lshlrev_b64 v[32:33], 1, v[32:33]
	v_cvt_pk_bf16_f32 v16, v16, v17
	v_cvt_pk_bf16_f32 v17, v18, v19
	v_lshl_add_u64 v[18:19], s[12:13], 0, v[32:33]
	global_store_dwordx2 v[18:19], v[16:17], off
	s_waitcnt vmcnt(22)
	v_pk_add_f32 v[18:19], v[94:95], v[42:43]
	v_pk_add_f32 v[16:17], v[92:93], v[40:41]
	v_add_f32_e32 v34, v34, v35
	v_mul_f32_e32 v35, v17, v17
	v_mul_f32_e32 v40, v19, v19
	global_store_dwordx4 v[148:149], v[16:19], off offset:64
	v_fmac_f32_e32 v35, v16, v16
	v_fmac_f32_e32 v40, v18, v18
	v_pk_mul_f32 v[18:19], v[10:11], v[18:19]
	v_pk_mul_f32 v[16:17], v[8:9], v[16:17]
	v_add_f32_e32 v35, v35, v40
	v_cvt_pk_bf16_f32 v16, v16, v17
	v_cvt_pk_bf16_f32 v17, v18, v19
	v_or_b32_e32 v18, 32, v32
	v_mov_b32_e32 v19, v33
	v_lshl_add_u64 v[18:19], s[12:13], 0, v[18:19]
	global_store_dwordx2 v[18:19], v[16:17], off
	s_waitcnt vmcnt(23)
	v_pk_add_f32 v[18:19], v[90:91], v[30:31]
	v_pk_add_f32 v[16:17], v[88:89], v[28:29]
	v_mul_f32_e32 v29, v19, v19
	v_mul_f32_e32 v28, v17, v17
	global_store_dwordx4 v[148:149], v[16:19], off offset:512
	v_fmac_f32_e32 v28, v16, v16
	v_fmac_f32_e32 v29, v18, v18
	v_pk_mul_f32 v[18:19], v[6:7], v[18:19]
	v_pk_mul_f32 v[16:17], v[4:5], v[16:17]
	v_add_f32_e32 v34, v34, v35
	v_cvt_pk_bf16_f32 v16, v16, v17
	v_cvt_pk_bf16_f32 v17, v18, v19
	v_or_b32_e32 v18, 0x100, v32
	v_mov_b32_e32 v19, v33
	v_lshl_add_u64 v[18:19], s[12:13], 0, v[18:19]
	global_store_dwordx2 v[18:19], v[16:17], off
	s_waitcnt vmcnt(24)
	v_pk_add_f32 v[18:19], v[86:87], v[22:23]
	v_pk_add_f32 v[16:17], v[84:85], v[20:21]
	v_mul_f32_e32 v21, v19, v19
	v_mul_f32_e32 v20, v17, v17
	v_add_f32_e32 v28, v28, v29
	v_fmac_f32_e32 v20, v16, v16
	v_fmac_f32_e32 v21, v18, v18
	v_add_f32_e32 v28, v34, v28
	v_add_f32_e32 v20, v20, v21
	v_add_f32_e32 v21, v28, v20
	ds_bpermute_b32 v22, v227, v21
	global_store_dwordx4 v[148:149], v[16:19], off offset:576
	v_or_b32_e32 v32, 0x120, v32
	s_nop 0
	v_pk_mul_f32 v[16:17], v[0:1], v[16:17]
	v_pk_mul_f32 v[18:19], v[2:3], v[18:19]
	v_cvt_pk_bf16_f32 v20, v16, v17
	s_waitcnt lgkmcnt(0)
	v_add_f32_e32 v16, v21, v22
	ds_bpermute_b32 v17, v226, v16
	v_cvt_pk_bf16_f32 v21, v18, v19
	v_lshl_add_u64 v[18:19], s[12:13], 0, v[32:33]
	global_store_dwordx2 v[18:19], v[20:21], off
	s_and_saveexec_b64 s[24:25], s[2:3]
	s_cbranch_execz .LBB0_1074
	v_lshl_add_u64 v[18:19], v[146:147], 2, s[14:15]
	s_waitcnt lgkmcnt(0)
	v_add_f32_e32 v16, v16, v17
	v_mov_b32_e32 v248, v16
.LBB0_1074:
	s_or_b64 exec, exec, s[24:25]
	s_waitcnt lgkmcnt(0)
	v_lshlrev_b64 v[16:17], 11, v[64:65]
	v_lshl_add_u64 v[20:21], v[16:17], 0, v[144:145]
	s_waitcnt vmcnt(17)
	v_pk_add_f32 v[16:17], v[80:81], v[60:61]
	v_pk_add_f32 v[18:19], v[82:83], v[62:63]
	v_mul_f32_e32 v22, v17, v17
	global_store_dwordx4 v[66:67], v[16:19], off
	v_fmac_f32_e32 v22, v16, v16
	v_pk_mul_f32 v[14:15], v[14:15], v[18:19]
	v_pk_mul_f32 v[12:13], v[12:13], v[16:17]
	v_lshlrev_b64 v[16:17], 1, v[20:21]
	v_cvt_pk_bf16_f32 v12, v12, v13
	v_cvt_pk_bf16_f32 v13, v14, v15
	v_lshl_add_u64 v[14:15], s[12:13], 0, v[16:17]
	global_store_dwordx2 v[14:15], v[12:13], off
	s_waitcnt vmcnt(18)
	v_pk_add_f32 v[14:15], v[78:79], v[50:51]
	v_pk_add_f32 v[12:13], v[76:77], v[48:49]
	v_pk_mul_f32 v[10:11], v[10:11], v[14:15]
	v_pk_mul_f32 v[8:9], v[8:9], v[12:13]
	global_store_dwordx4 v[66:67], v[12:15], off offset:64
	v_cvt_pk_bf16_f32 v8, v8, v9
	v_cvt_pk_bf16_f32 v9, v10, v11
	v_or_b32_e32 v10, 32, v16
	v_mov_b32_e32 v11, v17
	v_lshl_add_u64 v[10:11], s[12:13], 0, v[10:11]
	global_store_dwordx2 v[10:11], v[8:9], off
	s_waitcnt vmcnt(19)
	v_pk_add_f32 v[10:11], v[74:75], v[38:39]
	v_pk_add_f32 v[8:9], v[72:73], v[36:37]
	v_pk_mul_f32 v[6:7], v[6:7], v[10:11]
	v_pk_mul_f32 v[4:5], v[4:5], v[8:9]
	v_mul_f32_e32 v23, v19, v19
	v_cvt_pk_bf16_f32 v4, v4, v5
	v_cvt_pk_bf16_f32 v5, v6, v7
	v_or_b32_e32 v6, 0x100, v16
	v_mov_b32_e32 v7, v17
	v_fmac_f32_e32 v23, v18, v18
	v_mul_f32_e32 v18, v13, v13
	v_mul_f32_e32 v19, v15, v15
	v_lshl_add_u64 v[6:7], s[12:13], 0, v[6:7]
	v_fmac_f32_e32 v18, v12, v12
	v_fmac_f32_e32 v19, v14, v14
	global_store_dwordx4 v[66:67], v[8:11], off offset:512
	v_mul_f32_e32 v12, v9, v9
	v_mul_f32_e32 v13, v11, v11
	global_store_dwordx2 v[6:7], v[4:5], off
	s_waitcnt vmcnt(20)
	v_pk_add_f32 v[6:7], v[70:71], v[26:27]
	v_pk_add_f32 v[4:5], v[68:69], v[24:25]
	v_add_f32_e32 v22, v22, v23
	v_add_f32_e32 v18, v18, v19
	v_fmac_f32_e32 v12, v8, v8
	v_fmac_f32_e32 v13, v10, v10
	v_mul_f32_e32 v8, v5, v5
	v_mul_f32_e32 v9, v7, v7
	v_add_f32_e32 v18, v22, v18
	v_add_f32_e32 v12, v12, v13
	v_fmac_f32_e32 v8, v4, v4
	v_fmac_f32_e32 v9, v6, v6
	v_add_f32_e32 v12, v18, v12
	v_add_f32_e32 v8, v8, v9
	v_add_f32_e32 v8, v12, v8
	ds_bpermute_b32 v9, v227, v8
	v_pk_mul_f32 v[0:1], v[0:1], v[4:5]
	global_store_dwordx4 v[66:67], v[4:7], off offset:576
	v_pk_mul_f32 v[2:3], v[2:3], v[6:7]
	v_or_b32_e32 v16, 0x120, v16
	v_cvt_pk_bf16_f32 v4, v0, v1
	s_waitcnt lgkmcnt(0)
	v_add_f32_e32 v0, v8, v9
	ds_bpermute_b32 v1, v226, v0
	v_cvt_pk_bf16_f32 v5, v2, v3
	v_lshl_add_u64 v[2:3], s[12:13], 0, v[16:17]
	global_store_dwordx2 v[2:3], v[4:5], off
	s_and_saveexec_b64 s[24:25], s[2:3]
	s_cbranch_execz .LBB0_1076
	v_lshl_add_u64 v[2:3], v[64:65], 2, s[14:15]
	s_waitcnt lgkmcnt(0)
	v_add_f32_e32 v0, v0, v1
	global_atomic_add_f32 v[2:3], v0, off
	global_atomic_add_f32 v[2:3], v242, off offset:-704
	global_atomic_add_f32 v[2:3], v243, off offset:-640
	global_atomic_add_f32 v[2:3], v244, off offset:-576
	global_atomic_add_f32 v[2:3], v245, off offset:-512
	global_atomic_add_f32 v[2:3], v246, off offset:-192
	global_atomic_add_f32 v[2:3], v247, off offset:-128
	global_atomic_add_f32 v[2:3], v248, off offset:-64
